# v19
# speedup vs baseline: 1.0100x; 1.0100x over previous
; #define PG8_STAGE(bufoff, gbase, voff) do { const __amdgpu_buffer_rsrc_t _rs = __builtin_amdgcn_make_buffer_rsrc((void*)(gbase), 0, 0x7fffffff, 0x00020000); _Pragma("unroll") for (int _i = 0; _i < 2; ++_i) \
;         __builtin_amdgcn_raw_ptr_buffer_load_lds(_rs, (LAS unsigned*)(lds + (bufoff) + ldsw + _i * 8192), 16, (int)(voff)[_i], 0, 0, 0); } while (0)
; #define PG8_WAIT_V(n) asm volatile("s_waitcnt vmcnt(" #n ")" ::: "memory")
; #define PG8_WAIT_L(n) asm volatile("s_waitcnt lgkmcnt(" #n ")" ::: "memory")
; #define PG8_BAR __builtin_amdgcn_s_barrier()
; #define PG8_SCHED __builtin_amdgcn_sched_barrier(0)
; template <class Epi, class Sched, bool F8 = false>
; __device__ __forceinline__ void gemm_phase(LAS unsigned char* lds, const int lda, const int ldb, const Sched& S, const Epi& E) {
;     ...
;             PG8_LDB(B0, 0, 0); PG8_LDB(B1, 0, 1); PG8_SCHED; PG8_LDA(At, 0, 0); PG8_STAGE(PG8_SA(1, 1), a1 + hstepA, voffA);
;             PG8_WAIT_V(8); PG8_WAIT_L(0); PG8_BAR; PG8_MMA(0, 0, At, B0); PG8_MMA(0, 1, At, B1); PG8_BAR; PG8_SCHED;
;             PG8_LDA(At, 0, 1); PG8_STAGE(PG8_SB(0, 0), b2, voffB); PG8_STAGE(PG8_SB(0, 1), b2 + hstepB, voffB); PG8_STAGE(PG8_SA(0, 0), a2, voffA);
;             PG8_WAIT_V(8); PG8_WAIT_L(0); PG8_BAR; PG8_MMA(1, 0, At, B0); PG8_MMA(1, 1, At, B1); PG8_BAR; PG8_SCHED;
.LBB0_116:
	ds_read_b128 v[132:135], v140
	ds_read_b128 v[146:149], v140 offset:1024
	ds_read_b128 v[150:153], v140 offset:2048
	ds_read_b128 v[154:157], v140 offset:3072
	ds_read_b128 v[158:161], v141
	ds_read_b128 v[162:165], v141 offset:1024
	ds_read_b128 v[166:169], v141 offset:2048
	ds_read_b128 v[174:177], v141 offset:3072
	s_add_u32 s16, s63, 0xfff00080
	s_addc_u32 s17, s67, -1
	s_cmp_eq_u32 s69, 60
	s_cselect_b32 s28, s70, s16
	s_cselect_b32 s23, s71, s17
	s_cselect_b32 s22, s73, s62
	s_cselect_b32 s24, s72, s7
	s_add_u32 s20, s28, 0x80
	s_addc_u32 s21, s23, 0
	s_and_b32 s17, s67, 0xffff
	s_mov_b32 s16, s63
	s_mov_b32 m0, s93
	ds_read_b128 v[178:181], v142
	ds_read_b128 v[182:185], v142 offset:1024
	ds_read_b128 v[186:189], v142 offset:2048
	ds_read_b128 v[190:193], v142 offset:3072
	ds_read_b128 v[194:197], v142 offset:4096
	ds_read_b128 v[198:201], v142 offset:5120
	ds_read_b128 v[202:205], v142 offset:6144
	ds_read_b128 v[206:209], v142 offset:7168
	buffer_load_dwordx4 v136, s[16:19], 0 offen lds
	s_mov_b32 m0, s94
	s_nop 0
	buffer_load_dwordx4 v138, s[16:19], 0 offen lds
	s_waitcnt vmcnt(8)
	s_waitcnt lgkmcnt(0)
	s_setprio 1
	s_barrier
	v_mfma_f32_16x16x32_bf16 v[124:127], v[132:135], v[178:181], v[124:127]
	v_mfma_f32_16x16x32_bf16 v[120:123], v[150:153], v[178:181], v[120:123]
	v_mfma_f32_16x16x32_bf16 v[108:111], v[132:135], v[186:189], v[108:111]
	v_mfma_f32_16x16x32_bf16 v[104:107], v[150:153], v[186:189], v[104:107]
	v_mfma_f32_16x16x32_bf16 v[92:95], v[132:135], v[194:197], v[92:95]
	v_mfma_f32_16x16x32_bf16 v[88:91], v[150:153], v[194:197], v[88:91]
	v_mfma_f32_16x16x32_bf16 v[76:79], v[132:135], v[202:205], v[76:79]
	v_mfma_f32_16x16x32_bf16 v[72:75], v[150:153], v[202:205], v[72:75]
	v_mfma_f32_16x16x32_bf16 v[124:127], v[146:149], v[182:185], v[124:127]
	v_mfma_f32_16x16x32_bf16 v[120:123], v[154:157], v[182:185], v[120:123]
	v_mfma_f32_16x16x32_bf16 v[108:111], v[146:149], v[190:193], v[108:111]
	v_mfma_f32_16x16x32_bf16 v[104:107], v[154:157], v[190:193], v[104:107]
	v_mfma_f32_16x16x32_bf16 v[92:95], v[146:149], v[198:201], v[92:95]
	v_mfma_f32_16x16x32_bf16 v[88:91], v[154:157], v[198:201], v[88:91]
	v_mfma_f32_16x16x32_bf16 v[76:79], v[146:149], v[206:209], v[76:79]
	v_mfma_f32_16x16x32_bf16 v[72:75], v[154:157], v[206:209], v[72:75]
	s_setprio 0
	s_setprio 1
	v_mfma_f32_16x16x32_bf16 v[116:119], v[158:161], v[178:181], v[116:119]
	v_mfma_f32_16x16x32_bf16 v[112:115], v[166:169], v[178:181], v[112:115]
	v_mfma_f32_16x16x32_bf16 v[100:103], v[158:161], v[186:189], v[100:103]
	v_mfma_f32_16x16x32_bf16 v[96:99], v[166:169], v[186:189], v[96:99]
	v_mfma_f32_16x16x32_bf16 v[84:87], v[158:161], v[194:197], v[84:87]
	v_mfma_f32_16x16x32_bf16 v[80:83], v[166:169], v[194:197], v[80:83]
	v_mfma_f32_16x16x32_bf16 v[68:71], v[158:161], v[202:205], v[68:71]
	v_mfma_f32_16x16x32_bf16 v[64:67], v[166:169], v[202:205], v[64:67]
	v_mfma_f32_16x16x32_bf16 v[116:119], v[162:165], v[182:185], v[116:119]
	v_mfma_f32_16x16x32_bf16 v[112:115], v[174:177], v[182:185], v[112:115]
	v_mfma_f32_16x16x32_bf16 v[100:103], v[162:165], v[190:193], v[100:103]
	v_mfma_f32_16x16x32_bf16 v[96:99], v[174:177], v[190:193], v[96:99]
	v_mfma_f32_16x16x32_bf16 v[84:87], v[162:165], v[198:201], v[84:87]
	v_mfma_f32_16x16x32_bf16 v[80:83], v[174:177], v[198:201], v[80:83]
	v_mfma_f32_16x16x32_bf16 v[68:71], v[162:165], v[206:209], v[68:71]
	v_mfma_f32_16x16x32_bf16 v[64:67], v[174:177], v[206:209], v[64:67]
	s_barrier
	s_setprio 0
	s_and_b32 s25, s22, 0xffff
	s_mov_b32 m0, s8
	s_mov_b32 s26, s18
	s_mov_b32 s27, s19
	s_add_u32 s16, s24, 0x4000
	ds_read_b128 v[178:181], v142 offset:16384
	ds_read_b128 v[182:185], v142 offset:17408
	ds_read_b128 v[186:189], v142 offset:18432
	ds_read_b128 v[190:193], v142 offset:19456
	ds_read_b128 v[194:197], v142 offset:20480
	ds_read_b128 v[198:201], v142 offset:21504
	ds_read_b128 v[202:205], v142 offset:22528
	ds_read_b128 v[206:209], v142 offset:23552
	buffer_load_dwordx4 v137, s[24:27], 0 offen lds
	s_mov_b32 m0, s9
	s_addc_u32 s17, s22, 0
	buffer_load_dwordx4 v139, s[24:27], 0 offen lds
	s_and_b32 s17, s17, 0xffff
	s_mov_b32 m0, s76
	s_and_b32 s29, s23, 0xffff
	buffer_load_dwordx4 v137, s[16:19], 0 offen lds
	s_mov_b32 m0, s79
	s_mov_b32 s30, s18
	buffer_load_dwordx4 v139, s[16:19], 0 offen lds
	s_mov_b32 s31, s19
	s_mov_b32 m0, s3
	s_nop 0
	buffer_load_dwordx4 v136, s[28:31], 0 offen lds
	s_mov_b32 m0, s80
	s_nop 0
	buffer_load_dwordx4 v138, s[28:31], 0 offen lds
	s_waitcnt vmcnt(8)
	s_waitcnt lgkmcnt(0)
	s_setprio 1
	s_barrier
; #define PG8_STAGE(bufoff, gbase, voff) do { const __amdgpu_buffer_rsrc_t _rs = __builtin_amdgcn_make_buffer_rsrc((void*)(gbase), 0, 0x7fffffff, 0x00020000); _Pragma("unroll") for (int _i = 0; _i < 2; ++_i) \
;         __builtin_amdgcn_raw_ptr_buffer_load_lds(_rs, (LAS unsigned*)(lds + (bufoff) + ldsw + _i * 8192), 16, (int)(voff)[_i], 0, 0, 0); } while (0)
; #define PG8_WAIT_V(n) asm volatile("s_waitcnt vmcnt(" #n ")" ::: "memory")
; #define PG8_WAIT_L(n) asm volatile("s_waitcnt lgkmcnt(" #n ")" ::: "memory")
; #define PG8_BAR __builtin_amdgcn_s_barrier()
; #define PG8_SCHED __builtin_amdgcn_sched_barrier(0)
; template <class Epi, class Sched, bool F8 = false>
; __device__ __forceinline__ void gemm_phase(LAS unsigned char* lds, const int lda, const int ldb, const Sched& S, const Epi& E) {
;     ...
;             PG8_LDA(At, 0, 1); PG8_STAGE(PG8_SB(0, 0), b2, voffB); PG8_STAGE(PG8_SB(0, 1), b2 + hstepB, voffB); PG8_STAGE(PG8_SA(0, 0), a2, voffA);
;             PG8_WAIT_V(8); PG8_WAIT_L(0); PG8_BAR; PG8_MMA(1, 0, At, B0); PG8_MMA(1, 1, At, B1); PG8_BAR; PG8_SCHED;
;             PG8_LDB(B0, 1, 0); PG8_LDB(B1, 1, 1); PG8_SCHED; PG8_LDA(At, 1, 0); PG8_STAGE(PG8_SA(0, 1), a2 + hstepA, voffA);
;             PG8_WAIT_V(8); PG8_WAIT_L(0); PG8_BAR; PG8_MMA(0, 0, At, B0); PG8_MMA(0, 1, At, B1); PG8_BAR; PG8_SCHED;
	v_mfma_f32_16x16x32_bf16 v[60:63], v[132:135], v[178:181], v[60:63]
	v_mfma_f32_16x16x32_bf16 v[56:59], v[150:153], v[178:181], v[56:59]
	v_mfma_f32_16x16x32_bf16 v[44:47], v[132:135], v[186:189], v[44:47]
	v_mfma_f32_16x16x32_bf16 v[40:43], v[150:153], v[186:189], v[40:43]
	v_mfma_f32_16x16x32_bf16 v[28:31], v[132:135], v[194:197], v[28:31]
	v_mfma_f32_16x16x32_bf16 v[24:27], v[150:153], v[194:197], v[24:27]
	v_mfma_f32_16x16x32_bf16 v[12:15], v[132:135], v[202:205], v[12:15]
	v_mfma_f32_16x16x32_bf16 v[8:11], v[150:153], v[202:205], v[8:11]
	v_mfma_f32_16x16x32_bf16 v[60:63], v[146:149], v[182:185], v[60:63]
	v_mfma_f32_16x16x32_bf16 v[56:59], v[154:157], v[182:185], v[56:59]
	v_mfma_f32_16x16x32_bf16 v[44:47], v[146:149], v[190:193], v[44:47]
	v_mfma_f32_16x16x32_bf16 v[40:43], v[154:157], v[190:193], v[40:43]
	v_mfma_f32_16x16x32_bf16 v[28:31], v[146:149], v[198:201], v[28:31]
	v_mfma_f32_16x16x32_bf16 v[24:27], v[154:157], v[198:201], v[24:27]
	v_mfma_f32_16x16x32_bf16 v[12:15], v[146:149], v[206:209], v[12:15]
	v_mfma_f32_16x16x32_bf16 v[8:11], v[154:157], v[206:209], v[8:11]
	s_setprio 0
	s_setprio 1
	v_mfma_f32_16x16x32_bf16 v[52:55], v[158:161], v[178:181], v[52:55]
	v_mfma_f32_16x16x32_bf16 v[48:51], v[166:169], v[178:181], v[48:51]
	v_mfma_f32_16x16x32_bf16 v[36:39], v[158:161], v[186:189], v[36:39]
	v_mfma_f32_16x16x32_bf16 v[32:35], v[166:169], v[186:189], v[32:35]
	v_mfma_f32_16x16x32_bf16 v[20:23], v[158:161], v[194:197], v[20:23]
	v_mfma_f32_16x16x32_bf16 v[16:19], v[166:169], v[194:197], v[16:19]
	v_mfma_f32_16x16x32_bf16 v[4:7], v[158:161], v[202:205], v[4:7]
	v_mfma_f32_16x16x32_bf16 v[0:3], v[166:169], v[202:205], v[0:3]
	v_mfma_f32_16x16x32_bf16 v[52:55], v[162:165], v[182:185], v[52:55]
	v_mfma_f32_16x16x32_bf16 v[48:51], v[174:177], v[182:185], v[48:51]
	v_mfma_f32_16x16x32_bf16 v[36:39], v[162:165], v[190:193], v[36:39]
	v_mfma_f32_16x16x32_bf16 v[32:35], v[174:177], v[190:193], v[32:35]
	v_mfma_f32_16x16x32_bf16 v[20:23], v[162:165], v[198:201], v[20:23]
	v_mfma_f32_16x16x32_bf16 v[16:19], v[174:177], v[198:201], v[16:19]
	v_mfma_f32_16x16x32_bf16 v[4:7], v[162:165], v[206:209], v[4:7]
	v_mfma_f32_16x16x32_bf16 v[0:3], v[174:177], v[206:209], v[0:3]
	s_barrier
	s_setprio 0
	ds_read_b128 v[132:135], v143
	ds_read_b128 v[146:149], v143 offset:1024
	ds_read_b128 v[150:153], v143 offset:2048
	ds_read_b128 v[154:157], v143 offset:3072
	ds_read_b128 v[158:161], v144
	ds_read_b128 v[162:165], v144 offset:1024
	ds_read_b128 v[166:169], v144 offset:2048
	ds_read_b128 v[174:177], v144 offset:3072
	s_add_u32 s16, s28, 0x100000
	s_addc_u32 s17, s23, 0
	s_and_b32 s17, s17, 0xffff
	s_mov_b32 m0, s81
	ds_read_b128 v[178:181], v142 offset:32768
	ds_read_b128 v[182:185], v142 offset:33792
	ds_read_b128 v[186:189], v142 offset:34816
	ds_read_b128 v[190:193], v142 offset:35840
	ds_read_b128 v[194:197], v142 offset:36864
	ds_read_b128 v[198:201], v142 offset:37888
	ds_read_b128 v[202:205], v142 offset:38912
	ds_read_b128 v[206:209], v142 offset:39936
	buffer_load_dwordx4 v136, s[16:19], 0 offen lds
	s_mov_b32 m0, s82
	s_nop 0
	buffer_load_dwordx4 v138, s[16:19], 0 offen lds
	s_waitcnt vmcnt(8)
	s_waitcnt lgkmcnt(0)
	s_setprio 1
	s_barrier
	v_mfma_f32_16x16x32_bf16 v[124:127], v[132:135], v[178:181], v[124:127]
	v_mfma_f32_16x16x32_bf16 v[120:123], v[150:153], v[178:181], v[120:123]
	v_mfma_f32_16x16x32_bf16 v[108:111], v[132:135], v[186:189], v[108:111]
	v_mfma_f32_16x16x32_bf16 v[104:107], v[150:153], v[186:189], v[104:107]
	v_mfma_f32_16x16x32_bf16 v[92:95], v[132:135], v[194:197], v[92:95]
	v_mfma_f32_16x16x32_bf16 v[88:91], v[150:153], v[194:197], v[88:91]
	v_mfma_f32_16x16x32_bf16 v[76:79], v[132:135], v[202:205], v[76:79]
	v_mfma_f32_16x16x32_bf16 v[72:75], v[150:153], v[202:205], v[72:75]
	v_mfma_f32_16x16x32_bf16 v[124:127], v[146:149], v[182:185], v[124:127]
	v_mfma_f32_16x16x32_bf16 v[120:123], v[154:157], v[182:185], v[120:123]
	v_mfma_f32_16x16x32_bf16 v[108:111], v[146:149], v[190:193], v[108:111]
	v_mfma_f32_16x16x32_bf16 v[104:107], v[154:157], v[190:193], v[104:107]
	v_mfma_f32_16x16x32_bf16 v[92:95], v[146:149], v[198:201], v[92:95]
	v_mfma_f32_16x16x32_bf16 v[88:91], v[154:157], v[198:201], v[88:91]
	v_mfma_f32_16x16x32_bf16 v[76:79], v[146:149], v[206:209], v[76:79]
	v_mfma_f32_16x16x32_bf16 v[72:75], v[154:157], v[206:209], v[72:75]
	s_setprio 0
	s_setprio 1
	v_mfma_f32_16x16x32_bf16 v[116:119], v[158:161], v[178:181], v[116:119]
	v_mfma_f32_16x16x32_bf16 v[112:115], v[166:169], v[178:181], v[112:115]
	v_mfma_f32_16x16x32_bf16 v[100:103], v[158:161], v[186:189], v[100:103]
	v_mfma_f32_16x16x32_bf16 v[96:99], v[166:169], v[186:189], v[96:99]
	v_mfma_f32_16x16x32_bf16 v[84:87], v[158:161], v[194:197], v[84:87]
	v_mfma_f32_16x16x32_bf16 v[80:83], v[166:169], v[194:197], v[80:83]
	v_mfma_f32_16x16x32_bf16 v[68:71], v[158:161], v[202:205], v[68:71]
	v_mfma_f32_16x16x32_bf16 v[64:67], v[166:169], v[202:205], v[64:67]
	v_mfma_f32_16x16x32_bf16 v[116:119], v[162:165], v[182:185], v[116:119]
	v_mfma_f32_16x16x32_bf16 v[112:115], v[174:177], v[182:185], v[112:115]
	v_mfma_f32_16x16x32_bf16 v[100:103], v[162:165], v[190:193], v[100:103]
	v_mfma_f32_16x16x32_bf16 v[96:99], v[174:177], v[190:193], v[96:99]
	v_mfma_f32_16x16x32_bf16 v[84:87], v[162:165], v[198:201], v[84:87]
	v_mfma_f32_16x16x32_bf16 v[80:83], v[174:177], v[198:201], v[80:83]
	v_mfma_f32_16x16x32_bf16 v[68:71], v[162:165], v[206:209], v[68:71]
	v_mfma_f32_16x16x32_bf16 v[64:67], v[174:177], v[206:209], v[64:67]
	s_barrier
; #define PG8_STAGE(bufoff, gbase, voff) do { const __amdgpu_buffer_rsrc_t _rs = __builtin_amdgcn_make_buffer_rsrc((void*)(gbase), 0, 0x7fffffff, 0x00020000); _Pragma("unroll") for (int _i = 0; _i < 2; ++_i) \
;         __builtin_amdgcn_raw_ptr_buffer_load_lds(_rs, (LAS unsigned*)(lds + (bufoff) + ldsw + _i * 8192), 16, (int)(voff)[_i], 0, 0, 0); } while (0)
; #define PG8_WAIT_V(n) asm volatile("s_waitcnt vmcnt(" #n ")" ::: "memory")
; #define PG8_WAIT_L(n) asm volatile("s_waitcnt lgkmcnt(" #n ")" ::: "memory")
; #define PG8_BAR __builtin_amdgcn_s_barrier()
; #define PG8_SCHED __builtin_amdgcn_sched_barrier(0)
; template <class Epi, class Sched, bool F8 = false>
; __device__ __forceinline__ void gemm_phase(LAS unsigned char* lds, const int lda, const int ldb, const Sched& S, const Epi& E) {
;     ...
;             PG8_LDA(At, 1, 1); PG8_STAGE(PG8_SB(1, 0), b3, voffB); PG8_STAGE(PG8_SB(1, 1), b3 + hstepB, voffB); PG8_STAGE(PG8_SA(1, 0), a3, voffA);
;             PG8_WAIT_V(8); PG8_WAIT_L(0); PG8_BAR; PG8_MMA(1, 0, At, B0); PG8_MMA(1, 1, At, B1); PG8_BAR; PG8_SCHED;
	s_setprio 0
	s_add_u32 s16, s24, 0x8000
	s_addc_u32 s17, s22, 0
	s_mov_b32 m0, s87
	s_and_b32 s17, s17, 0xffff
	ds_read_b128 v[178:181], v142 offset:49152
	ds_read_b128 v[182:185], v142 offset:50176
	ds_read_b128 v[186:189], v142 offset:51200
	ds_read_b128 v[190:193], v142 offset:52224
	ds_read_b128 v[194:197], v142 offset:53248
	ds_read_b128 v[198:201], v142 offset:54272
	ds_read_b128 v[202:205], v142 offset:55296
	ds_read_b128 v[206:209], v142 offset:56320
	buffer_load_dwordx4 v137, s[16:19], 0 offen lds
	s_mov_b32 m0, s88
	s_mov_b32 s23, s19
	buffer_load_dwordx4 v139, s[16:19], 0 offen lds
	s_add_u32 s16, s24, 0xc000
	s_addc_u32 s17, s22, 0
	s_and_b32 s17, s17, 0xffff
	s_mov_b32 m0, s91
	s_and_b32 s21, s21, 0xffff
	buffer_load_dwordx4 v137, s[16:19], 0 offen lds
	s_mov_b32 m0, s92
	s_mov_b32 s22, s18
	buffer_load_dwordx4 v139, s[16:19], 0 offen lds
	s_mov_b32 m0, s89
	s_nop 0
	buffer_load_dwordx4 v136, s[20:23], 0 offen lds
	s_mov_b32 m0, s90
	s_nop 0
	buffer_load_dwordx4 v138, s[20:23], 0 offen lds
	s_waitcnt vmcnt(8)
	s_waitcnt lgkmcnt(0)
	s_setprio 1
	s_barrier
	v_mfma_f32_16x16x32_bf16 v[60:63], v[132:135], v[178:181], v[60:63]
	v_mfma_f32_16x16x32_bf16 v[56:59], v[150:153], v[178:181], v[56:59]
	v_mfma_f32_16x16x32_bf16 v[44:47], v[132:135], v[186:189], v[44:47]
	v_mfma_f32_16x16x32_bf16 v[40:43], v[150:153], v[186:189], v[40:43]
	v_mfma_f32_16x16x32_bf16 v[28:31], v[132:135], v[194:197], v[28:31]
	v_mfma_f32_16x16x32_bf16 v[24:27], v[150:153], v[194:197], v[24:27]
	v_mfma_f32_16x16x32_bf16 v[12:15], v[132:135], v[202:205], v[12:15]
	v_mfma_f32_16x16x32_bf16 v[8:11], v[150:153], v[202:205], v[8:11]
	v_mfma_f32_16x16x32_bf16 v[60:63], v[146:149], v[182:185], v[60:63]
	v_mfma_f32_16x16x32_bf16 v[56:59], v[154:157], v[182:185], v[56:59]
	v_mfma_f32_16x16x32_bf16 v[44:47], v[146:149], v[190:193], v[44:47]
	v_mfma_f32_16x16x32_bf16 v[40:43], v[154:157], v[190:193], v[40:43]
	v_mfma_f32_16x16x32_bf16 v[28:31], v[146:149], v[198:201], v[28:31]
	v_mfma_f32_16x16x32_bf16 v[24:27], v[154:157], v[198:201], v[24:27]
	v_mfma_f32_16x16x32_bf16 v[12:15], v[146:149], v[206:209], v[12:15]
	v_mfma_f32_16x16x32_bf16 v[8:11], v[154:157], v[206:209], v[8:11]
	s_setprio 0
	s_setprio 1
	v_mfma_f32_16x16x32_bf16 v[52:55], v[158:161], v[178:181], v[52:55]
	v_mfma_f32_16x16x32_bf16 v[48:51], v[166:169], v[178:181], v[48:51]
	v_mfma_f32_16x16x32_bf16 v[36:39], v[158:161], v[186:189], v[36:39]
	v_mfma_f32_16x16x32_bf16 v[32:35], v[166:169], v[186:189], v[32:35]
	v_mfma_f32_16x16x32_bf16 v[20:23], v[158:161], v[194:197], v[20:23]
	v_mfma_f32_16x16x32_bf16 v[16:19], v[166:169], v[194:197], v[16:19]
	v_mfma_f32_16x16x32_bf16 v[4:7], v[158:161], v[202:205], v[4:7]
	v_mfma_f32_16x16x32_bf16 v[0:3], v[166:169], v[202:205], v[0:3]
	v_mfma_f32_16x16x32_bf16 v[52:55], v[162:165], v[182:185], v[52:55]
	v_mfma_f32_16x16x32_bf16 v[48:51], v[174:177], v[182:185], v[48:51]
	v_mfma_f32_16x16x32_bf16 v[36:39], v[162:165], v[190:193], v[36:39]
	v_mfma_f32_16x16x32_bf16 v[32:35], v[174:177], v[190:193], v[32:35]
	v_mfma_f32_16x16x32_bf16 v[20:23], v[162:165], v[198:201], v[20:23]
	v_mfma_f32_16x16x32_bf16 v[16:19], v[174:177], v[198:201], v[16:19]
	v_mfma_f32_16x16x32_bf16 v[4:7], v[162:165], v[206:209], v[4:7]
	v_mfma_f32_16x16x32_bf16 v[0:3], v[174:177], v[206:209], v[0:3]
	s_barrier
	s_setprio 0
	s_add_i32 s69, s69, 2
	s_add_u32 s7, s7, 0x10000
	s_addc_u32 s62, s62, 0
	s_add_u32 s63, s63, 0x100
	s_addc_u32 s67, s67, 0
	s_cmp_gt_u32 s69, 61
	s_cbranch_scc0 .LBB0_116
	s_and_b64 vcc, exec, s[38:39]
	s_cbranch_vccz .LBB0_119
	s_barrier

; #define PG8_STAGE(bufoff, gbase, voff) do { const __amdgpu_buffer_rsrc_t _rs = __builtin_amdgcn_make_buffer_rsrc((void*)(gbase), 0, 0x7fffffff, 0x00020000); _Pragma("unroll") for (int _i = 0; _i < 2; ++_i) \
;         __builtin_amdgcn_raw_ptr_buffer_load_lds(_rs, (LAS unsigned*)(lds + (bufoff) + ldsw + _i * 8192), 16, (int)(voff)[_i], 0, 0, 0); } while (0)
; #define PG8_WAIT_V(n) asm volatile("s_waitcnt vmcnt(" #n ")" ::: "memory")
; #define PG8_WAIT_L(n) asm volatile("s_waitcnt lgkmcnt(" #n ")" ::: "memory")
; #define PG8_BAR __builtin_amdgcn_s_barrier()
; #define PG8_SCHED __builtin_amdgcn_sched_barrier(0)
; template <class Epi, class Sched, bool F8 = false>
; __device__ __forceinline__ void gemm_phase(LAS unsigned char* lds, const int lda, const int ldb, const Sched& S, const Epi& E) {
;     ...
;             PG8_LDB(B0, 0, 0); PG8_LDB(B1, 0, 1); PG8_SCHED; PG8_LDA(At, 0, 0); PG8_STAGE(PG8_SA(1, 1), a1 + hstepA, voffA);
;             PG8_WAIT_V(8); PG8_WAIT_L(0); PG8_BAR; PG8_MMA(0, 0, At, B0); PG8_MMA(0, 1, At, B1); PG8_BAR; PG8_SCHED;
;             PG8_LDA(At, 0, 1); PG8_STAGE(PG8_SB(0, 0), b2, voffB); PG8_STAGE(PG8_SB(0, 1), b2 + hstepB, voffB); PG8_STAGE(PG8_SA(0, 0), a2, voffA);
;             PG8_WAIT_V(8); PG8_WAIT_L(0); PG8_BAR; PG8_MMA(1, 0, At, B0); PG8_MMA(1, 1, At, B1); PG8_BAR; PG8_SCHED;
.LBB0_174:
	ds_read_b128 v[146:149], v140
	ds_read_b128 v[150:153], v140 offset:1024
	ds_read_b128 v[154:157], v140 offset:2048
	ds_read_b128 v[158:161], v140 offset:3072
	ds_read_b128 v[162:165], v141
	ds_read_b128 v[166:169], v141 offset:1024
	ds_read_b128 v[174:177], v141 offset:2048
	ds_read_b128 v[178:181], v141 offset:3072
	s_add_u32 s16, s63, 0xfff80080
	s_addc_u32 s17, s67, -1
	s_cmp_eq_u32 s69, 28
	s_cselect_b32 s28, s70, s16
	s_cselect_b32 s23, s71, s17
	s_cselect_b32 s22, s73, s62
	s_cselect_b32 s24, s72, s7
	s_add_u32 s20, s28, 0x80
	s_addc_u32 s21, s23, 0
	s_and_b32 s17, s67, 0xffff
	s_mov_b32 s16, s63
	s_mov_b32 m0, s96
	ds_read_b128 v[182:185], v142
	ds_read_b128 v[186:189], v142 offset:1024
	ds_read_b128 v[190:193], v142 offset:2048
	ds_read_b128 v[194:197], v142 offset:3072
	ds_read_b128 v[198:201], v142 offset:4096
	ds_read_b128 v[202:205], v142 offset:5120
	ds_read_b128 v[206:209], v142 offset:6144
	ds_read_b128 v[210:213], v142 offset:7168
	buffer_load_dwordx4 v136, s[16:19], 0 offen lds
	s_mov_b32 m0, s97
	s_nop 0
	buffer_load_dwordx4 v138, s[16:19], 0 offen lds
	s_waitcnt vmcnt(8)
	s_waitcnt lgkmcnt(0)
	s_setprio 1
	s_barrier
	v_mfma_scale_f32_16x16x128_f8f6f4 v[124:127], v[146:153], v[182:189], v[124:127], v143, v143 op_sel_hi:[0,0,0]
	v_mfma_scale_f32_16x16x128_f8f6f4 v[120:123], v[154:161], v[182:189], v[120:123], v143, v143 op_sel_hi:[0,0,0]
	v_mfma_scale_f32_16x16x128_f8f6f4 v[108:111], v[146:153], v[190:197], v[108:111], v143, v143 op_sel_hi:[0,0,0]
	v_mfma_scale_f32_16x16x128_f8f6f4 v[104:107], v[154:161], v[190:197], v[104:107], v143, v143 op_sel_hi:[0,0,0]
	v_mfma_scale_f32_16x16x128_f8f6f4 v[132:135], v[146:153], v[198:205], v[92:95], v143, v143 op_sel_hi:[0,0,0]
	v_mfma_scale_f32_16x16x128_f8f6f4 v[214:217], v[154:161], v[198:205], v[88:91], v143, v143 op_sel_hi:[0,0,0]
	v_mfma_scale_f32_16x16x128_f8f6f4 v[218:221], v[146:153], v[206:213], v[76:79], v143, v143 op_sel_hi:[0,0,0]
	v_mfma_scale_f32_16x16x128_f8f6f4 v[222:225], v[154:161], v[206:213], v[72:75], v143, v143 op_sel_hi:[0,0,0]
	s_setprio 0
	s_setprio 1
	v_mfma_scale_f32_16x16x128_f8f6f4 v[116:119], v[162:169], v[182:189], v[116:119], v143, v143 op_sel_hi:[0,0,0]
	v_mfma_scale_f32_16x16x128_f8f6f4 v[112:115], v[174:181], v[182:189], v[112:115], v143, v143 op_sel_hi:[0,0,0]
	v_mfma_scale_f32_16x16x128_f8f6f4 v[100:103], v[162:169], v[190:197], v[100:103], v143, v143 op_sel_hi:[0,0,0]
	v_mfma_scale_f32_16x16x128_f8f6f4 v[96:99], v[174:181], v[190:197], v[96:99], v143, v143 op_sel_hi:[0,0,0]
	v_mfma_scale_f32_16x16x128_f8f6f4 v[182:185], v[162:169], v[198:205], v[84:87], v143, v143 op_sel_hi:[0,0,0]
	v_mfma_scale_f32_16x16x128_f8f6f4 v[186:189], v[174:181], v[198:205], v[80:83], v143, v143 op_sel_hi:[0,0,0]
	v_mfma_scale_f32_16x16x128_f8f6f4 v[190:193], v[162:169], v[206:213], v[68:71], v143, v143 op_sel_hi:[0,0,0]
	v_mfma_scale_f32_16x16x128_f8f6f4 v[194:197], v[174:181], v[206:213], v[64:67], v143, v143 op_sel_hi:[0,0,0]
	s_barrier
	s_setprio 0
	s_and_b32 s25, s22, 0xffff
	s_mov_b32 m0, s79
	s_mov_b32 s26, s18
	s_mov_b32 s27, s19
	s_add_u32 s16, s24, 0x4000
	ds_read_b128 v[64:67], v142 offset:16384
	ds_read_b128 v[68:71], v142 offset:17408
	ds_read_b128 v[72:75], v142 offset:18432
	ds_read_b128 v[76:79], v142 offset:19456
	ds_read_b128 v[80:83], v142 offset:20480
	ds_read_b128 v[84:87], v142 offset:21504
	ds_read_b128 v[88:91], v142 offset:22528
	ds_read_b128 v[92:95], v142 offset:23552
	buffer_load_dwordx4 v137, s[24:27], 0 offen lds
	s_mov_b32 m0, s80
	s_addc_u32 s17, s22, 0
	buffer_load_dwordx4 v139, s[24:27], 0 offen lds
	s_and_b32 s17, s17, 0xffff
	s_mov_b32 m0, s81
	s_and_b32 s29, s23, 0xffff
	buffer_load_dwordx4 v137, s[16:19], 0 offen lds
	s_mov_b32 m0, s82
	s_mov_b32 s30, s18
	buffer_load_dwordx4 v139, s[16:19], 0 offen lds
	s_mov_b32 s31, s19
	s_mov_b32 m0, s76
	s_nop 0
	buffer_load_dwordx4 v136, s[28:31], 0 offen lds
	s_mov_b32 m0, s83
	s_nop 0
	buffer_load_dwordx4 v138, s[28:31], 0 offen lds
	s_waitcnt vmcnt(8)
	s_waitcnt lgkmcnt(0)
	s_setprio 1
	s_barrier
	v_mfma_scale_f32_16x16x128_f8f6f4 v[60:63], v[146:153], v[64:71], v[60:63], v143, v143 op_sel_hi:[0,0,0]
	v_mfma_scale_f32_16x16x128_f8f6f4 v[56:59], v[154:161], v[64:71], v[56:59], v143, v143 op_sel_hi:[0,0,0]
	v_mfma_scale_f32_16x16x128_f8f6f4 v[198:201], v[146:153], v[72:79], v[44:47], v143, v143 op_sel_hi:[0,0,0]
	v_mfma_scale_f32_16x16x128_f8f6f4 v[202:205], v[154:161], v[72:79], v[40:43], v143, v143 op_sel_hi:[0,0,0]
	v_mfma_scale_f32_16x16x128_f8f6f4 v[206:209], v[146:153], v[80:87], v[28:31], v143, v143 op_sel_hi:[0,0,0]
	v_mfma_scale_f32_16x16x128_f8f6f4 v[210:213], v[154:161], v[80:87], v[24:27], v143, v143 op_sel_hi:[0,0,0]
	v_mfma_scale_f32_16x16x128_f8f6f4 v[226:229], v[146:153], v[88:95], v[12:15], v143, v143 op_sel_hi:[0,0,0]
	v_mfma_scale_f32_16x16x128_f8f6f4 v[230:233], v[154:161], v[88:95], v[8:11], v143, v143 op_sel_hi:[0,0,0]
	s_setprio 0
	s_setprio 1
	v_mfma_scale_f32_16x16x128_f8f6f4 v[52:55], v[162:169], v[64:71], v[52:55], v143, v143 op_sel_hi:[0,0,0]
	v_mfma_scale_f32_16x16x128_f8f6f4 v[48:51], v[174:181], v[64:71], v[48:51], v143, v143 op_sel_hi:[0,0,0]
	v_mfma_scale_f32_16x16x128_f8f6f4 v[234:237], v[162:169], v[72:79], v[36:39], v143, v143 op_sel_hi:[0,0,0]
	v_mfma_scale_f32_16x16x128_f8f6f4 v[238:241], v[174:181], v[72:79], v[32:35], v143, v143 op_sel_hi:[0,0,0]
	v_mfma_scale_f32_16x16x128_f8f6f4 v[242:245], v[162:169], v[80:87], v[20:23], v143, v143 op_sel_hi:[0,0,0]
	v_mfma_scale_f32_16x16x128_f8f6f4 v[246:249], v[174:181], v[80:87], v[16:19], v143, v143 op_sel_hi:[0,0,0]
	v_mfma_scale_f32_16x16x128_f8f6f4 v[250:253], v[162:169], v[88:95], v[4:7], v143, v143 op_sel_hi:[0,0,0]
	v_mfma_scale_f32_16x16x128_f8f6f4 v[170:173], v[174:181], v[88:95], v[0:3], v143, v143 op_sel_hi:[0,0,0]
	s_barrier
; #define PG8_STAGE(bufoff, gbase, voff) do { const __amdgpu_buffer_rsrc_t _rs = __builtin_amdgcn_make_buffer_rsrc((void*)(gbase), 0, 0x7fffffff, 0x00020000); _Pragma("unroll") for (int _i = 0; _i < 2; ++_i) \
;         __builtin_amdgcn_raw_ptr_buffer_load_lds(_rs, (LAS unsigned*)(lds + (bufoff) + ldsw + _i * 8192), 16, (int)(voff)[_i], 0, 0, 0); } while (0)
; #define PG8_WAIT_V(n) asm volatile("s_waitcnt vmcnt(" #n ")" ::: "memory")
; #define PG8_WAIT_L(n) asm volatile("s_waitcnt lgkmcnt(" #n ")" ::: "memory")
; #define PG8_BAR __builtin_amdgcn_s_barrier()
; #define PG8_SCHED __builtin_amdgcn_sched_barrier(0)
; template <class Epi, class Sched, bool F8 = false>
; __device__ __forceinline__ void gemm_phase(LAS unsigned char* lds, const int lda, const int ldb, const Sched& S, const Epi& E) {
;     ...
;             PG8_LDB(B0, 1, 0); PG8_LDB(B1, 1, 1); PG8_SCHED; PG8_LDA(At, 1, 0); PG8_STAGE(PG8_SA(0, 1), a2 + hstepA, voffA);
;             PG8_WAIT_V(8); PG8_WAIT_L(0); PG8_BAR; PG8_MMA(0, 0, At, B0); PG8_MMA(0, 1, At, B1); PG8_BAR; PG8_SCHED;
;             PG8_LDA(At, 1, 1); PG8_STAGE(PG8_SB(1, 0), b3, voffB); PG8_STAGE(PG8_SB(1, 1), b3 + hstepB, voffB); PG8_STAGE(PG8_SA(1, 0), a3, voffA);
;             PG8_WAIT_V(8); PG8_WAIT_L(0); PG8_BAR; PG8_MMA(1, 0, At, B0); PG8_MMA(1, 1, At, B1); PG8_BAR; PG8_SCHED;
	s_setprio 0
	s_nop 4
	ds_read_b128 v[0:3], v144
	ds_read_b128 v[4:7], v144 offset:1024
	ds_read_b128 v[16:19], v144 offset:2048
	ds_read_b128 v[20:23], v144 offset:3072
	ds_read_b128 v[146:149], v145
	ds_read_b128 v[150:153], v145 offset:1024
	ds_read_b128 v[154:157], v145 offset:2048
	ds_read_b128 v[158:161], v145 offset:3072
	s_add_u32 s16, s28, 0x80000
	s_addc_u32 s17, s23, 0
	s_and_b32 s17, s17, 0xffff
	s_mov_b32 m0, s84
	ds_read_b128 v[8:11], v142 offset:32768
	ds_read_b128 v[12:15], v142 offset:33792
	ds_read_b128 v[24:27], v142 offset:34816
	ds_read_b128 v[28:31], v142 offset:35840
	ds_read_b128 v[32:35], v142 offset:36864
	ds_read_b128 v[36:39], v142 offset:37888
	ds_read_b128 v[40:43], v142 offset:38912
	ds_read_b128 v[44:47], v142 offset:39936
	buffer_load_dwordx4 v136, s[16:19], 0 offen lds
	s_mov_b32 m0, s85
	s_nop 0
	buffer_load_dwordx4 v138, s[16:19], 0 offen lds
	s_waitcnt vmcnt(8)
	s_waitcnt lgkmcnt(0)
	s_setprio 1
	s_barrier
	v_mfma_scale_f32_16x16x128_f8f6f4 v[124:127], v[0:7], v[8:15], v[124:127], v143, v143 op_sel_hi:[0,0,0]
	v_mfma_scale_f32_16x16x128_f8f6f4 v[120:123], v[16:23], v[8:15], v[120:123], v143, v143 op_sel_hi:[0,0,0]
	v_mfma_scale_f32_16x16x128_f8f6f4 v[108:111], v[0:7], v[24:31], v[108:111], v143, v143 op_sel_hi:[0,0,0]
	v_mfma_scale_f32_16x16x128_f8f6f4 v[104:107], v[16:23], v[24:31], v[104:107], v143, v143 op_sel_hi:[0,0,0]
	v_mfma_scale_f32_16x16x128_f8f6f4 v[92:95], v[0:7], v[32:39], v[132:135], v143, v143 op_sel_hi:[0,0,0]
	v_mfma_scale_f32_16x16x128_f8f6f4 v[88:91], v[16:23], v[32:39], v[214:217], v143, v143 op_sel_hi:[0,0,0]
	v_mfma_scale_f32_16x16x128_f8f6f4 v[76:79], v[0:7], v[40:47], v[218:221], v143, v143 op_sel_hi:[0,0,0]
	v_mfma_scale_f32_16x16x128_f8f6f4 v[72:75], v[16:23], v[40:47], v[222:225], v143, v143 op_sel_hi:[0,0,0]
	s_setprio 0
	s_setprio 1
	v_mfma_scale_f32_16x16x128_f8f6f4 v[116:119], v[146:153], v[8:15], v[116:119], v143, v143 op_sel_hi:[0,0,0]
	v_mfma_scale_f32_16x16x128_f8f6f4 v[112:115], v[154:161], v[8:15], v[112:115], v143, v143 op_sel_hi:[0,0,0]
	v_mfma_scale_f32_16x16x128_f8f6f4 v[100:103], v[146:153], v[24:31], v[100:103], v143, v143 op_sel_hi:[0,0,0]
	v_mfma_scale_f32_16x16x128_f8f6f4 v[96:99], v[154:161], v[24:31], v[96:99], v143, v143 op_sel_hi:[0,0,0]
	v_mfma_scale_f32_16x16x128_f8f6f4 v[84:87], v[146:153], v[32:39], v[182:185], v143, v143 op_sel_hi:[0,0,0]
	v_mfma_scale_f32_16x16x128_f8f6f4 v[80:83], v[154:161], v[32:39], v[186:189], v143, v143 op_sel_hi:[0,0,0]
	v_mfma_scale_f32_16x16x128_f8f6f4 v[68:71], v[146:153], v[40:47], v[190:193], v143, v143 op_sel_hi:[0,0,0]
	v_mfma_scale_f32_16x16x128_f8f6f4 v[64:67], v[154:161], v[40:47], v[194:197], v143, v143 op_sel_hi:[0,0,0]
	s_barrier
	s_setprio 0
	s_add_u32 s16, s24, 0x8000
	s_addc_u32 s17, s22, 0
	s_mov_b32 m0, s90
	s_and_b32 s17, s17, 0xffff
	ds_read_b128 v[32:35], v142 offset:49152
	ds_read_b128 v[36:39], v142 offset:50176
	ds_read_b128 v[162:165], v142 offset:51200
	ds_read_b128 v[166:169], v142 offset:52224
	ds_read_b128 v[174:177], v142 offset:53248
	ds_read_b128 v[178:181], v142 offset:54272
	ds_read_b128 v[182:185], v142 offset:55296
	ds_read_b128 v[186:189], v142 offset:56320
	buffer_load_dwordx4 v137, s[16:19], 0 offen lds
	s_mov_b32 m0, s91
	s_mov_b32 s23, s19
	buffer_load_dwordx4 v139, s[16:19], 0 offen lds
	s_add_u32 s16, s24, 0xc000
	s_addc_u32 s17, s22, 0
	s_and_b32 s17, s17, 0xffff
	s_mov_b32 m0, s94
	s_and_b32 s21, s21, 0xffff
	buffer_load_dwordx4 v137, s[16:19], 0 offen lds
	s_mov_b32 m0, s95
	s_mov_b32 s22, s18
	buffer_load_dwordx4 v139, s[16:19], 0 offen lds
	s_mov_b32 m0, s92
	s_nop 0
	buffer_load_dwordx4 v136, s[20:23], 0 offen lds
	s_mov_b32 m0, s93
	s_nop 0
	buffer_load_dwordx4 v138, s[20:23], 0 offen lds
	s_waitcnt vmcnt(8)
	s_waitcnt lgkmcnt(0)
	s_setprio 1
	s_barrier
	v_mfma_scale_f32_16x16x128_f8f6f4 v[60:63], v[0:7], v[32:39], v[60:63], v143, v143 op_sel_hi:[0,0,0]
	v_mfma_scale_f32_16x16x128_f8f6f4 v[56:59], v[16:23], v[32:39], v[56:59], v143, v143 op_sel_hi:[0,0,0]
	v_mfma_scale_f32_16x16x128_f8f6f4 v[44:47], v[0:7], v[162:169], v[198:201], v143, v143 op_sel_hi:[0,0,0]
	v_mfma_scale_f32_16x16x128_f8f6f4 v[40:43], v[16:23], v[162:169], v[202:205], v143, v143 op_sel_hi:[0,0,0]
	v_mfma_scale_f32_16x16x128_f8f6f4 v[28:31], v[0:7], v[174:181], v[206:209], v143, v143 op_sel_hi:[0,0,0]
	v_mfma_scale_f32_16x16x128_f8f6f4 v[24:27], v[16:23], v[174:181], v[210:213], v143, v143 op_sel_hi:[0,0,0]
	v_mfma_scale_f32_16x16x128_f8f6f4 v[12:15], v[0:7], v[182:189], v[226:229], v143, v143 op_sel_hi:[0,0,0]
	v_mfma_scale_f32_16x16x128_f8f6f4 v[8:11], v[16:23], v[182:189], v[230:233], v143, v143 op_sel_hi:[0,0,0]
	s_setprio 0
	s_setprio 1
	v_mfma_scale_f32_16x16x128_f8f6f4 v[52:55], v[146:153], v[32:39], v[52:55], v143, v143 op_sel_hi:[0,0,0]
	v_mfma_scale_f32_16x16x128_f8f6f4 v[48:51], v[154:161], v[32:39], v[48:51], v143, v143 op_sel_hi:[0,0,0]
	v_mfma_scale_f32_16x16x128_f8f6f4 v[36:39], v[146:153], v[162:169], v[234:237], v143, v143 op_sel_hi:[0,0,0]
	v_mfma_scale_f32_16x16x128_f8f6f4 v[32:35], v[154:161], v[162:169], v[238:241], v143, v143 op_sel_hi:[0,0,0]
	v_mfma_scale_f32_16x16x128_f8f6f4 v[20:23], v[146:153], v[174:181], v[242:245], v143, v143 op_sel_hi:[0,0,0]
	v_mfma_scale_f32_16x16x128_f8f6f4 v[16:19], v[154:161], v[174:181], v[246:249], v143, v143 op_sel_hi:[0,0,0]
	v_mfma_scale_f32_16x16x128_f8f6f4 v[4:7], v[146:153], v[182:189], v[250:253], v143, v143 op_sel_hi:[0,0,0]
	v_mfma_scale_f32_16x16x128_f8f6f4 v[0:3], v[154:161], v[182:189], v[170:173], v143, v143 op_sel_hi:[0,0,0]
	s_barrier
	s_setprio 0
	s_add_i32 s69, s69, 2
	s_add_u32 s7, s7, 0x10000
	s_addc_u32 s62, s62, 0
	s_add_u32 s63, s63, 0x100
	s_addc_u32 s67, s67, 0
	s_cmp_gt_u32 s69, 29
	s_cbranch_scc0 .LBB0_174
	s_and_b64 vcc, exec, s[38:39]
	s_cbranch_vccz .LBB0_177
	s_barrier

; #define PG8_STAGE(bufoff, gbase, voff) do { const __amdgpu_buffer_rsrc_t _rs = __builtin_amdgcn_make_buffer_rsrc((void*)(gbase), 0, 0x7fffffff, 0x00020000); _Pragma("unroll") for (int _i = 0; _i < 2; ++_i) \
;         __builtin_amdgcn_raw_ptr_buffer_load_lds(_rs, (LAS unsigned*)(lds + (bufoff) + ldsw + _i * 8192), 16, (int)(voff)[_i], 0, 0, 0); } while (0)
; #define PG8_WAIT_V(n) asm volatile("s_waitcnt vmcnt(" #n ")" ::: "memory")
; #define PG8_WAIT_L(n) asm volatile("s_waitcnt lgkmcnt(" #n ")" ::: "memory")
; #define PG8_BAR __builtin_amdgcn_s_barrier()
; #define PG8_SCHED __builtin_amdgcn_sched_barrier(0)
; template <class Epi, class Sched, bool F8 = false>
; __device__ __forceinline__ void gemm_phase(LAS unsigned char* lds, const int lda, const int ldb, const Sched& S, const Epi& E) {
;     ...
;             PG8_LDB(B0, 0, 0); PG8_LDB(B1, 0, 1); PG8_SCHED; PG8_LDA(At, 0, 0); PG8_STAGE(PG8_SA(1, 1), a1 + hstepA, voffA);
;             PG8_WAIT_V(8); PG8_WAIT_L(0); PG8_BAR; PG8_MMA(0, 0, At, B0); PG8_MMA(0, 1, At, B1); PG8_BAR; PG8_SCHED;
;             PG8_LDA(At, 0, 1); PG8_STAGE(PG8_SB(0, 0), b2, voffB); PG8_STAGE(PG8_SB(0, 1), b2 + hstepB, voffB); PG8_STAGE(PG8_SA(0, 0), a2, voffA);
;             PG8_WAIT_V(8); PG8_WAIT_L(0); PG8_BAR; PG8_MMA(1, 0, At, B0); PG8_MMA(1, 1, At, B1); PG8_BAR; PG8_SCHED;
.LBB0_408:
	ds_read_b128 v[104:107], v180
	ds_read_b128 v[108:111], v180 offset:1024
	ds_read_b128 v[136:139], v180 offset:2048
	ds_read_b128 v[140:143], v180 offset:3072
	ds_read_b128 v[148:151], v181
	ds_read_b128 v[152:155], v181 offset:1024
	ds_read_b128 v[156:159], v181 offset:2048
	ds_read_b128 v[160:163], v181 offset:3072
	s_add_i32 s64, s4, 2
	s_add_u32 s5, vcc_hi, 0xfff80080
	s_addc_u32 s16, s35, -1
	s_cmp_eq_u32 s62, s4
	s_cselect_b32 s40, s70, s5
	s_cselect_b32 s19, s71, s16
	s_cselect_b32 s18, s73, vcc_lo
	s_cselect_b32 s36, s72, s63
	s_add_u32 s16, s40, 0x80
	s_addc_u32 s17, s19, 0
	s_and_b32 s5, s35, 0xffff
	s_mov_b32 s4, vcc_hi
	s_mov_b32 m0, s92
	ds_read_b128 v[164:167], v182
	ds_read_b128 v[168:171], v182 offset:1024
	ds_read_b128 v[172:175], v182 offset:2048
	ds_read_b128 v[186:189], v182 offset:3072
	ds_read_b128 v[190:193], v182 offset:4096
	ds_read_b128 v[194:197], v182 offset:5120
	ds_read_b128 v[198:201], v182 offset:6144
	ds_read_b128 v[202:205], v182 offset:7168
	buffer_load_dwordx4 v176, s[4:7], 0 offen lds
	s_mov_b32 m0, s93
	s_nop 0
	buffer_load_dwordx4 v178, s[4:7], 0 offen lds
	s_waitcnt vmcnt(8)
	s_waitcnt lgkmcnt(0)
	s_setprio 1
	s_barrier
	v_mfma_f32_16x16x32_bf16 v[132:135], v[104:107], v[164:167], v[132:135]
	v_mfma_f32_16x16x32_bf16 v[128:131], v[136:139], v[164:167], v[128:131]
	v_mfma_f32_16x16x32_bf16 v[124:127], v[104:107], v[172:175], v[124:127]
	v_mfma_f32_16x16x32_bf16 v[120:123], v[136:139], v[172:175], v[120:123]
	v_mfma_f32_16x16x32_bf16 v[116:119], v[104:107], v[190:193], v[116:119]
	v_mfma_f32_16x16x32_bf16 v[112:115], v[136:139], v[190:193], v[112:115]
	v_mfma_f32_16x16x32_bf16 v[100:103], v[104:107], v[198:201], v[100:103]
	v_mfma_f32_16x16x32_bf16 v[96:99], v[136:139], v[198:201], v[96:99]
	v_mfma_f32_16x16x32_bf16 v[132:135], v[108:111], v[168:171], v[132:135]
	v_mfma_f32_16x16x32_bf16 v[128:131], v[140:143], v[168:171], v[128:131]
	v_mfma_f32_16x16x32_bf16 v[124:127], v[108:111], v[186:189], v[124:127]
	v_mfma_f32_16x16x32_bf16 v[120:123], v[140:143], v[186:189], v[120:123]
	v_mfma_f32_16x16x32_bf16 v[116:119], v[108:111], v[194:197], v[116:119]
	v_mfma_f32_16x16x32_bf16 v[112:115], v[140:143], v[194:197], v[112:115]
	v_mfma_f32_16x16x32_bf16 v[100:103], v[108:111], v[202:205], v[100:103]
	v_mfma_f32_16x16x32_bf16 v[96:99], v[140:143], v[202:205], v[96:99]
	s_setprio 0
	s_setprio 1
	v_mfma_f32_16x16x32_bf16 v[60:63], v[148:151], v[164:167], v[60:63]
	v_mfma_f32_16x16x32_bf16 v[56:59], v[156:159], v[164:167], v[56:59]
	v_mfma_f32_16x16x32_bf16 v[52:55], v[148:151], v[172:175], v[52:55]
	v_mfma_f32_16x16x32_bf16 v[48:51], v[156:159], v[172:175], v[48:51]
	v_mfma_f32_16x16x32_bf16 v[44:47], v[148:151], v[190:193], v[44:47]
	v_mfma_f32_16x16x32_bf16 v[40:43], v[156:159], v[190:193], v[40:43]
	v_mfma_f32_16x16x32_bf16 v[36:39], v[148:151], v[198:201], v[36:39]
	v_mfma_f32_16x16x32_bf16 v[32:35], v[156:159], v[198:201], v[32:35]
	v_mfma_f32_16x16x32_bf16 v[60:63], v[152:155], v[168:171], v[60:63]
	v_mfma_f32_16x16x32_bf16 v[56:59], v[160:163], v[168:171], v[56:59]
	v_mfma_f32_16x16x32_bf16 v[52:55], v[152:155], v[186:189], v[52:55]
	v_mfma_f32_16x16x32_bf16 v[48:51], v[160:163], v[186:189], v[48:51]
	v_mfma_f32_16x16x32_bf16 v[44:47], v[152:155], v[194:197], v[44:47]
	v_mfma_f32_16x16x32_bf16 v[40:43], v[160:163], v[194:197], v[40:43]
	v_mfma_f32_16x16x32_bf16 v[36:39], v[152:155], v[202:205], v[36:39]
	v_mfma_f32_16x16x32_bf16 v[32:35], v[160:163], v[202:205], v[32:35]
	s_barrier
	s_setprio 0
	s_and_b32 s37, s18, 0xffff
	s_mov_b32 m0, s75
	s_mov_b32 s38, s6
	s_mov_b32 s39, s7
	s_add_u32 s4, s36, 0x4000
	ds_read_b128 v[164:167], v182 offset:16384
	ds_read_b128 v[168:171], v182 offset:17408
	ds_read_b128 v[172:175], v182 offset:18432
	ds_read_b128 v[186:189], v182 offset:19456
	ds_read_b128 v[190:193], v182 offset:20480
	ds_read_b128 v[194:197], v182 offset:21504
	ds_read_b128 v[198:201], v182 offset:22528
	ds_read_b128 v[202:205], v182 offset:23552
	buffer_load_dwordx4 v177, s[36:39], 0 offen lds
	s_mov_b32 m0, s77
	s_addc_u32 s5, s18, 0
	buffer_load_dwordx4 v179, s[36:39], 0 offen lds
	s_and_b32 s5, s5, 0xffff
	s_mov_b32 m0, s78
	s_and_b32 s41, s19, 0xffff
	buffer_load_dwordx4 v177, s[4:7], 0 offen lds
	s_mov_b32 m0, s79
	s_mov_b32 s42, s6
	buffer_load_dwordx4 v179, s[4:7], 0 offen lds
	s_mov_b32 s43, s7
	s_mov_b32 m0, s74
	s_nop 0
	buffer_load_dwordx4 v176, s[40:43], 0 offen lds
	s_mov_b32 m0, s80
	s_nop 0
	buffer_load_dwordx4 v178, s[40:43], 0 offen lds
	s_waitcnt vmcnt(8)
	s_waitcnt lgkmcnt(0)
	s_setprio 1
	s_barrier
; #define PG8_STAGE(bufoff, gbase, voff) do { const __amdgpu_buffer_rsrc_t _rs = __builtin_amdgcn_make_buffer_rsrc((void*)(gbase), 0, 0x7fffffff, 0x00020000); _Pragma("unroll") for (int _i = 0; _i < 2; ++_i) \
;         __builtin_amdgcn_raw_ptr_buffer_load_lds(_rs, (LAS unsigned*)(lds + (bufoff) + ldsw + _i * 8192), 16, (int)(voff)[_i], 0, 0, 0); } while (0)
; #define PG8_WAIT_V(n) asm volatile("s_waitcnt vmcnt(" #n ")" ::: "memory")
; #define PG8_WAIT_L(n) asm volatile("s_waitcnt lgkmcnt(" #n ")" ::: "memory")
; #define PG8_BAR __builtin_amdgcn_s_barrier()
; #define PG8_SCHED __builtin_amdgcn_sched_barrier(0)
; template <class Epi, class Sched, bool F8 = false>
; __device__ __forceinline__ void gemm_phase(LAS unsigned char* lds, const int lda, const int ldb, const Sched& S, const Epi& E) {
;     ...
;             PG8_LDA(At, 0, 1); PG8_STAGE(PG8_SB(0, 0), b2, voffB); PG8_STAGE(PG8_SB(0, 1), b2 + hstepB, voffB); PG8_STAGE(PG8_SA(0, 0), a2, voffA);
;             PG8_WAIT_V(8); PG8_WAIT_L(0); PG8_BAR; PG8_MMA(1, 0, At, B0); PG8_MMA(1, 1, At, B1); PG8_BAR; PG8_SCHED;
;             PG8_LDB(B0, 1, 0); PG8_LDB(B1, 1, 1); PG8_SCHED; PG8_LDA(At, 1, 0); PG8_STAGE(PG8_SA(0, 1), a2 + hstepA, voffA);
;             PG8_WAIT_V(8); PG8_WAIT_L(0); PG8_BAR; PG8_MMA(0, 0, At, B0); PG8_MMA(0, 1, At, B1); PG8_BAR; PG8_SCHED;
	v_mfma_f32_16x16x32_bf16 v[92:95], v[104:107], v[164:167], v[92:95]
	v_mfma_f32_16x16x32_bf16 v[88:91], v[136:139], v[164:167], v[88:91]
	v_mfma_f32_16x16x32_bf16 v[84:87], v[104:107], v[172:175], v[84:87]
	v_mfma_f32_16x16x32_bf16 v[80:83], v[136:139], v[172:175], v[80:83]
	v_mfma_f32_16x16x32_bf16 v[76:79], v[104:107], v[190:193], v[76:79]
	v_mfma_f32_16x16x32_bf16 v[72:75], v[136:139], v[190:193], v[72:75]
	v_mfma_f32_16x16x32_bf16 v[68:71], v[104:107], v[198:201], v[68:71]
	v_mfma_f32_16x16x32_bf16 v[64:67], v[136:139], v[198:201], v[64:67]
	v_mfma_f32_16x16x32_bf16 v[92:95], v[108:111], v[168:171], v[92:95]
	v_mfma_f32_16x16x32_bf16 v[88:91], v[140:143], v[168:171], v[88:91]
	v_mfma_f32_16x16x32_bf16 v[84:87], v[108:111], v[186:189], v[84:87]
	v_mfma_f32_16x16x32_bf16 v[80:83], v[140:143], v[186:189], v[80:83]
	v_mfma_f32_16x16x32_bf16 v[76:79], v[108:111], v[194:197], v[76:79]
	v_mfma_f32_16x16x32_bf16 v[72:75], v[140:143], v[194:197], v[72:75]
	v_mfma_f32_16x16x32_bf16 v[68:71], v[108:111], v[202:205], v[68:71]
	v_mfma_f32_16x16x32_bf16 v[64:67], v[140:143], v[202:205], v[64:67]
	s_setprio 0
	s_setprio 1
	v_mfma_f32_16x16x32_bf16 v[28:31], v[148:151], v[164:167], v[28:31]
	v_mfma_f32_16x16x32_bf16 v[24:27], v[156:159], v[164:167], v[24:27]
	v_mfma_f32_16x16x32_bf16 v[20:23], v[148:151], v[172:175], v[20:23]
	v_mfma_f32_16x16x32_bf16 v[16:19], v[156:159], v[172:175], v[16:19]
	v_mfma_f32_16x16x32_bf16 v[12:15], v[148:151], v[190:193], v[12:15]
	v_mfma_f32_16x16x32_bf16 v[8:11], v[156:159], v[190:193], v[8:11]
	v_mfma_f32_16x16x32_bf16 v[4:7], v[148:151], v[198:201], v[4:7]
	v_mfma_f32_16x16x32_bf16 v[0:3], v[156:159], v[198:201], v[0:3]
	v_mfma_f32_16x16x32_bf16 v[28:31], v[152:155], v[168:171], v[28:31]
	v_mfma_f32_16x16x32_bf16 v[24:27], v[160:163], v[168:171], v[24:27]
	v_mfma_f32_16x16x32_bf16 v[20:23], v[152:155], v[186:189], v[20:23]
	v_mfma_f32_16x16x32_bf16 v[16:19], v[160:163], v[186:189], v[16:19]
	v_mfma_f32_16x16x32_bf16 v[12:15], v[152:155], v[194:197], v[12:15]
	v_mfma_f32_16x16x32_bf16 v[8:11], v[160:163], v[194:197], v[8:11]
	v_mfma_f32_16x16x32_bf16 v[4:7], v[152:155], v[202:205], v[4:7]
	v_mfma_f32_16x16x32_bf16 v[0:3], v[160:163], v[202:205], v[0:3]
	s_barrier
	s_setprio 0
	ds_read_b128 v[104:107], v183
	ds_read_b128 v[108:111], v183 offset:1024
	ds_read_b128 v[136:139], v183 offset:2048
	ds_read_b128 v[140:143], v183 offset:3072
	ds_read_b128 v[148:151], v184
	ds_read_b128 v[152:155], v184 offset:1024
	ds_read_b128 v[156:159], v184 offset:2048
	ds_read_b128 v[160:163], v184 offset:3072
	s_add_u32 s4, s40, 0x80000
	s_addc_u32 s5, s19, 0
	s_and_b32 s5, s5, 0xffff
	s_mov_b32 m0, s81
	ds_read_b128 v[164:167], v182 offset:32768
	ds_read_b128 v[168:171], v182 offset:33792
	ds_read_b128 v[172:175], v182 offset:34816
	ds_read_b128 v[186:189], v182 offset:35840
	ds_read_b128 v[190:193], v182 offset:36864
	ds_read_b128 v[194:197], v182 offset:37888
	ds_read_b128 v[198:201], v182 offset:38912
	ds_read_b128 v[202:205], v182 offset:39936
	buffer_load_dwordx4 v176, s[4:7], 0 offen lds
	s_mov_b32 m0, s82
	s_nop 0
	buffer_load_dwordx4 v178, s[4:7], 0 offen lds
	s_waitcnt vmcnt(8)
	s_waitcnt lgkmcnt(0)
	s_setprio 1
	s_barrier
	v_mfma_f32_16x16x32_bf16 v[132:135], v[104:107], v[164:167], v[132:135]
	v_mfma_f32_16x16x32_bf16 v[128:131], v[136:139], v[164:167], v[128:131]
	v_mfma_f32_16x16x32_bf16 v[124:127], v[104:107], v[172:175], v[124:127]
	v_mfma_f32_16x16x32_bf16 v[120:123], v[136:139], v[172:175], v[120:123]
	v_mfma_f32_16x16x32_bf16 v[116:119], v[104:107], v[190:193], v[116:119]
	v_mfma_f32_16x16x32_bf16 v[112:115], v[136:139], v[190:193], v[112:115]
	v_mfma_f32_16x16x32_bf16 v[100:103], v[104:107], v[198:201], v[100:103]
	v_mfma_f32_16x16x32_bf16 v[96:99], v[136:139], v[198:201], v[96:99]
	v_mfma_f32_16x16x32_bf16 v[132:135], v[108:111], v[168:171], v[132:135]
	v_mfma_f32_16x16x32_bf16 v[128:131], v[140:143], v[168:171], v[128:131]
	v_mfma_f32_16x16x32_bf16 v[124:127], v[108:111], v[186:189], v[124:127]
	v_mfma_f32_16x16x32_bf16 v[120:123], v[140:143], v[186:189], v[120:123]
	v_mfma_f32_16x16x32_bf16 v[116:119], v[108:111], v[194:197], v[116:119]
	v_mfma_f32_16x16x32_bf16 v[112:115], v[140:143], v[194:197], v[112:115]
	v_mfma_f32_16x16x32_bf16 v[100:103], v[108:111], v[202:205], v[100:103]
	v_mfma_f32_16x16x32_bf16 v[96:99], v[140:143], v[202:205], v[96:99]
	s_setprio 0
	s_setprio 1
	v_mfma_f32_16x16x32_bf16 v[60:63], v[148:151], v[164:167], v[60:63]
	v_mfma_f32_16x16x32_bf16 v[56:59], v[156:159], v[164:167], v[56:59]
	v_mfma_f32_16x16x32_bf16 v[52:55], v[148:151], v[172:175], v[52:55]
	v_mfma_f32_16x16x32_bf16 v[48:51], v[156:159], v[172:175], v[48:51]
	v_mfma_f32_16x16x32_bf16 v[44:47], v[148:151], v[190:193], v[44:47]
	v_mfma_f32_16x16x32_bf16 v[40:43], v[156:159], v[190:193], v[40:43]
	v_mfma_f32_16x16x32_bf16 v[36:39], v[148:151], v[198:201], v[36:39]
	v_mfma_f32_16x16x32_bf16 v[32:35], v[156:159], v[198:201], v[32:35]
	v_mfma_f32_16x16x32_bf16 v[60:63], v[152:155], v[168:171], v[60:63]
	v_mfma_f32_16x16x32_bf16 v[56:59], v[160:163], v[168:171], v[56:59]
	v_mfma_f32_16x16x32_bf16 v[52:55], v[152:155], v[186:189], v[52:55]
	v_mfma_f32_16x16x32_bf16 v[48:51], v[160:163], v[186:189], v[48:51]
	v_mfma_f32_16x16x32_bf16 v[44:47], v[152:155], v[194:197], v[44:47]
	v_mfma_f32_16x16x32_bf16 v[40:43], v[160:163], v[194:197], v[40:43]
	v_mfma_f32_16x16x32_bf16 v[36:39], v[152:155], v[202:205], v[36:39]
	v_mfma_f32_16x16x32_bf16 v[32:35], v[160:163], v[202:205], v[32:35]
	s_barrier
; #define PG8_STAGE(bufoff, gbase, voff) do { const __amdgpu_buffer_rsrc_t _rs = __builtin_amdgcn_make_buffer_rsrc((void*)(gbase), 0, 0x7fffffff, 0x00020000); _Pragma("unroll") for (int _i = 0; _i < 2; ++_i) \
;         __builtin_amdgcn_raw_ptr_buffer_load_lds(_rs, (LAS unsigned*)(lds + (bufoff) + ldsw + _i * 8192), 16, (int)(voff)[_i], 0, 0, 0); } while (0)
; #define PG8_WAIT_V(n) asm volatile("s_waitcnt vmcnt(" #n ")" ::: "memory")
; #define PG8_WAIT_L(n) asm volatile("s_waitcnt lgkmcnt(" #n ")" ::: "memory")
; #define PG8_BAR __builtin_amdgcn_s_barrier()
; #define PG8_SCHED __builtin_amdgcn_sched_barrier(0)
; template <class Epi, class Sched, bool F8 = false>
; __device__ __forceinline__ void gemm_phase(LAS unsigned char* lds, const int lda, const int ldb, const Sched& S, const Epi& E) {
;     ...
;             PG8_LDA(At, 1, 1); PG8_STAGE(PG8_SB(1, 0), b3, voffB); PG8_STAGE(PG8_SB(1, 1), b3 + hstepB, voffB); PG8_STAGE(PG8_SA(1, 0), a3, voffA);
;             PG8_WAIT_V(8); PG8_WAIT_L(0); PG8_BAR; PG8_MMA(1, 0, At, B0); PG8_MMA(1, 1, At, B1); PG8_BAR; PG8_SCHED;
	s_setprio 0
	s_add_u32 s4, s36, 0x8000
	s_addc_u32 s5, s18, 0
	s_mov_b32 m0, s86
	s_and_b32 s5, s5, 0xffff
	ds_read_b128 v[164:167], v182 offset:49152
	ds_read_b128 v[168:171], v182 offset:50176
	ds_read_b128 v[172:175], v182 offset:51200
	ds_read_b128 v[186:189], v182 offset:52224
	ds_read_b128 v[190:193], v182 offset:53248
	ds_read_b128 v[194:197], v182 offset:54272
	ds_read_b128 v[198:201], v182 offset:55296
	ds_read_b128 v[202:205], v182 offset:56320
	buffer_load_dwordx4 v177, s[4:7], 0 offen lds
	s_mov_b32 m0, s87
	s_mov_b32 s19, s7
	buffer_load_dwordx4 v179, s[4:7], 0 offen lds
	s_add_u32 s4, s36, 0xc000
	s_addc_u32 s5, s18, 0
	s_and_b32 s5, s5, 0xffff
	s_mov_b32 m0, s90
	s_and_b32 s17, s17, 0xffff
	buffer_load_dwordx4 v177, s[4:7], 0 offen lds
	s_mov_b32 m0, s91
	s_mov_b32 s18, s6
	buffer_load_dwordx4 v179, s[4:7], 0 offen lds
	s_mov_b32 m0, s88
	s_nop 0
	buffer_load_dwordx4 v176, s[16:19], 0 offen lds
	s_mov_b32 m0, s89
	s_nop 0
	buffer_load_dwordx4 v178, s[16:19], 0 offen lds
	s_waitcnt vmcnt(8)
	s_waitcnt lgkmcnt(0)
	s_setprio 1
	s_barrier
	v_mfma_f32_16x16x32_bf16 v[92:95], v[104:107], v[164:167], v[92:95]
	v_mfma_f32_16x16x32_bf16 v[88:91], v[136:139], v[164:167], v[88:91]
	v_mfma_f32_16x16x32_bf16 v[84:87], v[104:107], v[172:175], v[84:87]
	v_mfma_f32_16x16x32_bf16 v[80:83], v[136:139], v[172:175], v[80:83]
	v_mfma_f32_16x16x32_bf16 v[76:79], v[104:107], v[190:193], v[76:79]
	v_mfma_f32_16x16x32_bf16 v[72:75], v[136:139], v[190:193], v[72:75]
	v_mfma_f32_16x16x32_bf16 v[68:71], v[104:107], v[198:201], v[68:71]
	v_mfma_f32_16x16x32_bf16 v[64:67], v[136:139], v[198:201], v[64:67]
	v_mfma_f32_16x16x32_bf16 v[92:95], v[108:111], v[168:171], v[92:95]
	v_mfma_f32_16x16x32_bf16 v[88:91], v[140:143], v[168:171], v[88:91]
	v_mfma_f32_16x16x32_bf16 v[84:87], v[108:111], v[186:189], v[84:87]
	v_mfma_f32_16x16x32_bf16 v[80:83], v[140:143], v[186:189], v[80:83]
	v_mfma_f32_16x16x32_bf16 v[76:79], v[108:111], v[194:197], v[76:79]
	v_mfma_f32_16x16x32_bf16 v[72:75], v[140:143], v[194:197], v[72:75]
	v_mfma_f32_16x16x32_bf16 v[68:71], v[108:111], v[202:205], v[68:71]
	v_mfma_f32_16x16x32_bf16 v[64:67], v[140:143], v[202:205], v[64:67]
	s_setprio 0
	s_setprio 1
	v_mfma_f32_16x16x32_bf16 v[28:31], v[148:151], v[164:167], v[28:31]
	v_mfma_f32_16x16x32_bf16 v[24:27], v[156:159], v[164:167], v[24:27]
	v_mfma_f32_16x16x32_bf16 v[20:23], v[148:151], v[172:175], v[20:23]
	v_mfma_f32_16x16x32_bf16 v[16:19], v[156:159], v[172:175], v[16:19]
	v_mfma_f32_16x16x32_bf16 v[12:15], v[148:151], v[190:193], v[12:15]
	v_mfma_f32_16x16x32_bf16 v[8:11], v[156:159], v[190:193], v[8:11]
	v_mfma_f32_16x16x32_bf16 v[4:7], v[148:151], v[198:201], v[4:7]
	v_mfma_f32_16x16x32_bf16 v[0:3], v[156:159], v[198:201], v[0:3]
	v_mfma_f32_16x16x32_bf16 v[28:31], v[152:155], v[168:171], v[28:31]
	v_mfma_f32_16x16x32_bf16 v[24:27], v[160:163], v[168:171], v[24:27]
	v_mfma_f32_16x16x32_bf16 v[20:23], v[152:155], v[186:189], v[20:23]
	v_mfma_f32_16x16x32_bf16 v[16:19], v[160:163], v[186:189], v[16:19]
	v_mfma_f32_16x16x32_bf16 v[12:15], v[152:155], v[194:197], v[12:15]
	v_mfma_f32_16x16x32_bf16 v[8:11], v[160:163], v[194:197], v[8:11]
	v_mfma_f32_16x16x32_bf16 v[4:7], v[152:155], v[202:205], v[4:7]
	v_mfma_f32_16x16x32_bf16 v[0:3], v[160:163], v[202:205], v[0:3]
	s_barrier
	s_setprio 0
	s_add_u32 s63, s63, 0x10000
	s_addc_u32 vcc_lo, vcc_lo, 0
	s_add_u32 vcc_hi, vcc_hi, 0x100
	s_addc_u32 s35, s35, 0
	s_cmp_ge_i32 s64, s9
	s_mov_b32 s4, s64
	s_cbranch_scc0 .LBB0_408
	s_and_b64 vcc, exec, s[66:67]
	s_cbranch_vccz .LBB0_411
	s_barrier

; #define PG8_STAGE(bufoff, gbase, voff) do { const __amdgpu_buffer_rsrc_t _rs = __builtin_amdgcn_make_buffer_rsrc((void*)(gbase), 0, 0x7fffffff, 0x00020000); _Pragma("unroll") for (int _i = 0; _i < 2; ++_i) \
;         __builtin_amdgcn_raw_ptr_buffer_load_lds(_rs, (LAS unsigned*)(lds + (bufoff) + ldsw + _i * 8192), 16, (int)(voff)[_i], 0, 0, 0); } while (0)
; #define PG8_WAIT_V(n) asm volatile("s_waitcnt vmcnt(" #n ")" ::: "memory")
; #define PG8_WAIT_L(n) asm volatile("s_waitcnt lgkmcnt(" #n ")" ::: "memory")
; #define PG8_BAR __builtin_amdgcn_s_barrier()
; #define PG8_SCHED __builtin_amdgcn_sched_barrier(0)
; template <class Epi, class Sched, bool F8 = false>
; __device__ __forceinline__ void gemm_phase(LAS unsigned char* lds, const int lda, const int ldb, const Sched& S, const Epi& E) {
;     ...
;             PG8_LDB(B0, 0, 0); PG8_LDB(B1, 0, 1); PG8_SCHED; PG8_LDA(At, 0, 0); PG8_STAGE(PG8_SA(1, 1), a1 + hstepA, voffA);
;             PG8_WAIT_V(8); PG8_WAIT_L(0); PG8_BAR; PG8_MMA(0, 0, At, B0); PG8_MMA(0, 1, At, B1); PG8_BAR; PG8_SCHED;
;             PG8_LDA(At, 0, 1); PG8_STAGE(PG8_SB(0, 0), b2, voffB); PG8_STAGE(PG8_SB(0, 1), b2 + hstepB, voffB); PG8_STAGE(PG8_SA(0, 0), a2, voffA);
;             PG8_WAIT_V(8); PG8_WAIT_L(0); PG8_BAR; PG8_MMA(1, 0, At, B0); PG8_MMA(1, 1, At, B1); PG8_BAR; PG8_SCHED;
.LBB0_485:
	v_add_u32_e32 v144, 0x10000, v152
	v_add_u32_e32 v166, 0x14000, v152
	ds_read_b128 v[132:135], v144
	ds_read_b128 v[136:139], v144 offset:1024
	ds_read_b128 v[140:143], v144 offset:2048
	ds_read_b128 v[144:147], v144 offset:3072
	ds_read_b128 v[154:157], v166
	ds_read_b128 v[158:161], v166 offset:1024
	ds_read_b128 v[162:165], v166 offset:2048
	ds_read_b128 v[166:169], v166 offset:3072
	s_add_u32 s4, s47, 0xfff80080
	s_addc_u32 s5, s62, -1
	s_cmp_eq_u32 s63, 28
	s_cselect_b32 s40, s48, s4
	s_cselect_b32 s19, s49, s5
	s_cselect_b32 s18, s51, s33
	s_cselect_b32 s36, s50, s9
	s_add_u32 s16, s40, 0x80
	s_addc_u32 s17, s19, 0
	s_and_b32 s5, s62, 0xffff
	s_mov_b32 s4, s47
	s_mov_b32 m0, s91
	ds_read_b128 v[170:173], v153
	ds_read_b128 v[174:177], v153 offset:1024
	ds_read_b128 v[178:181], v153 offset:2048
	ds_read_b128 v[182:185], v153 offset:3072
	ds_read_b128 v[186:189], v153 offset:4096
	ds_read_b128 v[190:193], v153 offset:5120
	ds_read_b128 v[194:197], v153 offset:6144
	ds_read_b128 v[198:201], v153 offset:7168
	buffer_load_dwordx4 v148, s[4:7], 0 offen lds
	s_mov_b32 m0, s92
	s_nop 0
	buffer_load_dwordx4 v150, s[4:7], 0 offen lds
	s_waitcnt vmcnt(8)
	s_waitcnt lgkmcnt(0)
	s_setprio 1
	s_barrier
	v_mfma_f32_16x16x32_bf16 v[124:127], v[132:135], v[170:173], v[124:127]
	v_mfma_f32_16x16x32_bf16 v[120:123], v[140:143], v[170:173], v[120:123]
	v_mfma_f32_16x16x32_bf16 v[116:119], v[132:135], v[178:181], v[116:119]
	v_mfma_f32_16x16x32_bf16 v[112:115], v[140:143], v[178:181], v[112:115]
	v_mfma_f32_16x16x32_bf16 v[108:111], v[132:135], v[186:189], v[108:111]
	v_mfma_f32_16x16x32_bf16 v[104:107], v[140:143], v[186:189], v[104:107]
	v_mfma_f32_16x16x32_bf16 v[100:103], v[132:135], v[194:197], v[100:103]
	v_mfma_f32_16x16x32_bf16 v[96:99], v[140:143], v[194:197], v[96:99]
	v_mfma_f32_16x16x32_bf16 v[124:127], v[136:139], v[174:177], v[124:127]
	v_mfma_f32_16x16x32_bf16 v[120:123], v[144:147], v[174:177], v[120:123]
	v_mfma_f32_16x16x32_bf16 v[116:119], v[136:139], v[182:185], v[116:119]
	v_mfma_f32_16x16x32_bf16 v[112:115], v[144:147], v[182:185], v[112:115]
	v_mfma_f32_16x16x32_bf16 v[108:111], v[136:139], v[190:193], v[108:111]
	v_mfma_f32_16x16x32_bf16 v[104:107], v[144:147], v[190:193], v[104:107]
	v_mfma_f32_16x16x32_bf16 v[100:103], v[136:139], v[198:201], v[100:103]
	v_mfma_f32_16x16x32_bf16 v[96:99], v[144:147], v[198:201], v[96:99]
	s_setprio 0
	s_setprio 1
	v_mfma_f32_16x16x32_bf16 v[92:95], v[154:157], v[170:173], v[92:95]
	v_mfma_f32_16x16x32_bf16 v[88:91], v[162:165], v[170:173], v[88:91]
	v_mfma_f32_16x16x32_bf16 v[84:87], v[154:157], v[178:181], v[84:87]
	v_mfma_f32_16x16x32_bf16 v[80:83], v[162:165], v[178:181], v[80:83]
	v_mfma_f32_16x16x32_bf16 v[76:79], v[154:157], v[186:189], v[76:79]
	v_mfma_f32_16x16x32_bf16 v[72:75], v[162:165], v[186:189], v[72:75]
	v_mfma_f32_16x16x32_bf16 v[68:71], v[154:157], v[194:197], v[68:71]
	v_mfma_f32_16x16x32_bf16 v[64:67], v[162:165], v[194:197], v[64:67]
	v_mfma_f32_16x16x32_bf16 v[92:95], v[158:161], v[174:177], v[92:95]
	v_mfma_f32_16x16x32_bf16 v[88:91], v[166:169], v[174:177], v[88:91]
	v_mfma_f32_16x16x32_bf16 v[84:87], v[158:161], v[182:185], v[84:87]
	v_mfma_f32_16x16x32_bf16 v[80:83], v[166:169], v[182:185], v[80:83]
	v_mfma_f32_16x16x32_bf16 v[76:79], v[158:161], v[190:193], v[76:79]
	v_mfma_f32_16x16x32_bf16 v[72:75], v[166:169], v[190:193], v[72:75]
	v_mfma_f32_16x16x32_bf16 v[68:71], v[158:161], v[198:201], v[68:71]
	v_mfma_f32_16x16x32_bf16 v[64:67], v[166:169], v[198:201], v[64:67]
	s_barrier
	s_setprio 0
	s_and_b32 s37, s18, 0xffff
	s_mov_b32 m0, s70
	s_mov_b32 s38, s6
	s_mov_b32 s39, s7
	s_add_u32 s4, s36, 0x4000
	ds_read_b128 v[170:173], v153 offset:16384
	ds_read_b128 v[174:177], v153 offset:17408
	ds_read_b128 v[178:181], v153 offset:18432
	ds_read_b128 v[182:185], v153 offset:19456
	ds_read_b128 v[186:189], v153 offset:20480
	ds_read_b128 v[190:193], v153 offset:21504
	ds_read_b128 v[194:197], v153 offset:22528
	ds_read_b128 v[198:201], v153 offset:23552
	buffer_load_dwordx4 v149, s[36:39], 0 offen lds
	s_mov_b32 m0, s71
	s_addc_u32 s5, s18, 0
	buffer_load_dwordx4 v151, s[36:39], 0 offen lds
	s_and_b32 s5, s5, 0xffff
	s_mov_b32 m0, s72
	s_and_b32 s41, s19, 0xffff
	buffer_load_dwordx4 v149, s[4:7], 0 offen lds
	s_mov_b32 m0, s73
	s_mov_b32 s42, s6
	buffer_load_dwordx4 v151, s[4:7], 0 offen lds
	s_mov_b32 s43, s7
	s_mov_b32 m0, s67
	s_nop 0
	buffer_load_dwordx4 v148, s[40:43], 0 offen lds
	s_mov_b32 m0, s74
	s_nop 0
	buffer_load_dwordx4 v150, s[40:43], 0 offen lds
	s_waitcnt vmcnt(8)
	s_waitcnt lgkmcnt(0)
	s_setprio 1
	s_barrier
; #define PG8_STAGE(bufoff, gbase, voff) do { const __amdgpu_buffer_rsrc_t _rs = __builtin_amdgcn_make_buffer_rsrc((void*)(gbase), 0, 0x7fffffff, 0x00020000); _Pragma("unroll") for (int _i = 0; _i < 2; ++_i) \
;         __builtin_amdgcn_raw_ptr_buffer_load_lds(_rs, (LAS unsigned*)(lds + (bufoff) + ldsw + _i * 8192), 16, (int)(voff)[_i], 0, 0, 0); } while (0)
; #define PG8_WAIT_V(n) asm volatile("s_waitcnt vmcnt(" #n ")" ::: "memory")
; #define PG8_WAIT_L(n) asm volatile("s_waitcnt lgkmcnt(" #n ")" ::: "memory")
; #define PG8_BAR __builtin_amdgcn_s_barrier()
; #define PG8_SCHED __builtin_amdgcn_sched_barrier(0)
; template <class Epi, class Sched, bool F8 = false>
; __device__ __forceinline__ void gemm_phase(LAS unsigned char* lds, const int lda, const int ldb, const Sched& S, const Epi& E) {
;     ...
;             PG8_LDA(At, 0, 1); PG8_STAGE(PG8_SB(0, 0), b2, voffB); PG8_STAGE(PG8_SB(0, 1), b2 + hstepB, voffB); PG8_STAGE(PG8_SA(0, 0), a2, voffA);
;             PG8_WAIT_V(8); PG8_WAIT_L(0); PG8_BAR; PG8_MMA(1, 0, At, B0); PG8_MMA(1, 1, At, B1); PG8_BAR; PG8_SCHED;
;             PG8_LDB(B0, 1, 0); PG8_LDB(B1, 1, 1); PG8_SCHED; PG8_LDA(At, 1, 0); PG8_STAGE(PG8_SA(0, 1), a2 + hstepA, voffA);
;             PG8_WAIT_V(8); PG8_WAIT_L(0); PG8_BAR; PG8_MMA(0, 0, At, B0); PG8_MMA(0, 1, At, B1); PG8_BAR; PG8_SCHED;
	v_mfma_f32_16x16x32_bf16 v[60:63], v[132:135], v[170:173], v[60:63]
	v_mfma_f32_16x16x32_bf16 v[56:59], v[140:143], v[170:173], v[56:59]
	v_mfma_f32_16x16x32_bf16 v[52:55], v[132:135], v[178:181], v[52:55]
	v_mfma_f32_16x16x32_bf16 v[48:51], v[140:143], v[178:181], v[48:51]
	v_mfma_f32_16x16x32_bf16 v[44:47], v[132:135], v[186:189], v[44:47]
	v_mfma_f32_16x16x32_bf16 v[40:43], v[140:143], v[186:189], v[40:43]
	v_mfma_f32_16x16x32_bf16 v[36:39], v[132:135], v[194:197], v[36:39]
	v_mfma_f32_16x16x32_bf16 v[32:35], v[140:143], v[194:197], v[32:35]
	v_mfma_f32_16x16x32_bf16 v[60:63], v[136:139], v[174:177], v[60:63]
	v_mfma_f32_16x16x32_bf16 v[56:59], v[144:147], v[174:177], v[56:59]
	v_mfma_f32_16x16x32_bf16 v[52:55], v[136:139], v[182:185], v[52:55]
	v_mfma_f32_16x16x32_bf16 v[48:51], v[144:147], v[182:185], v[48:51]
	v_mfma_f32_16x16x32_bf16 v[44:47], v[136:139], v[190:193], v[44:47]
	v_mfma_f32_16x16x32_bf16 v[40:43], v[144:147], v[190:193], v[40:43]
	v_mfma_f32_16x16x32_bf16 v[36:39], v[136:139], v[198:201], v[36:39]
	v_mfma_f32_16x16x32_bf16 v[32:35], v[144:147], v[198:201], v[32:35]
	s_setprio 0
	s_setprio 1
	v_mfma_f32_16x16x32_bf16 v[28:31], v[154:157], v[170:173], v[28:31]
	v_mfma_f32_16x16x32_bf16 v[24:27], v[162:165], v[170:173], v[24:27]
	v_mfma_f32_16x16x32_bf16 v[20:23], v[154:157], v[178:181], v[20:23]
	v_mfma_f32_16x16x32_bf16 v[16:19], v[162:165], v[178:181], v[16:19]
	v_mfma_f32_16x16x32_bf16 v[12:15], v[154:157], v[186:189], v[12:15]
	v_mfma_f32_16x16x32_bf16 v[8:11], v[162:165], v[186:189], v[8:11]
	v_mfma_f32_16x16x32_bf16 v[4:7], v[154:157], v[194:197], v[4:7]
	v_mfma_f32_16x16x32_bf16 v[0:3], v[162:165], v[194:197], v[0:3]
	v_mfma_f32_16x16x32_bf16 v[28:31], v[158:161], v[174:177], v[28:31]
	v_mfma_f32_16x16x32_bf16 v[24:27], v[166:169], v[174:177], v[24:27]
	v_mfma_f32_16x16x32_bf16 v[20:23], v[158:161], v[182:185], v[20:23]
	v_mfma_f32_16x16x32_bf16 v[16:19], v[166:169], v[182:185], v[16:19]
	v_mfma_f32_16x16x32_bf16 v[12:15], v[158:161], v[190:193], v[12:15]
	v_mfma_f32_16x16x32_bf16 v[8:11], v[166:169], v[190:193], v[8:11]
	v_mfma_f32_16x16x32_bf16 v[4:7], v[158:161], v[198:201], v[4:7]
	v_mfma_f32_16x16x32_bf16 v[0:3], v[166:169], v[198:201], v[0:3]
	s_barrier
	s_setprio 0
	v_add_u32_e32 v144, 0x18000, v152
	v_add_u32_e32 v166, 0x1c000, v152
	ds_read_b128 v[132:135], v144
	ds_read_b128 v[136:139], v144 offset:1024
	ds_read_b128 v[140:143], v144 offset:2048
	ds_read_b128 v[144:147], v144 offset:3072
	ds_read_b128 v[154:157], v166
	ds_read_b128 v[158:161], v166 offset:1024
	ds_read_b128 v[162:165], v166 offset:2048
	ds_read_b128 v[166:169], v166 offset:3072
	s_add_u32 s4, s40, 0x80000
	s_addc_u32 s5, s19, 0
	s_and_b32 s5, s5, 0xffff
	s_mov_b32 m0, s75
	ds_read_b128 v[170:173], v153 offset:32768
	ds_read_b128 v[174:177], v153 offset:33792
	ds_read_b128 v[178:181], v153 offset:34816
	ds_read_b128 v[182:185], v153 offset:35840
	ds_read_b128 v[186:189], v153 offset:36864
	ds_read_b128 v[190:193], v153 offset:37888
	ds_read_b128 v[194:197], v153 offset:38912
	ds_read_b128 v[198:201], v153 offset:39936
	buffer_load_dwordx4 v148, s[4:7], 0 offen lds
	s_mov_b32 m0, s76
	s_nop 0
	buffer_load_dwordx4 v150, s[4:7], 0 offen lds
	s_waitcnt vmcnt(8)
	s_waitcnt lgkmcnt(0)
	s_setprio 1
	s_barrier
	v_mfma_f32_16x16x32_bf16 v[124:127], v[132:135], v[170:173], v[124:127]
	v_mfma_f32_16x16x32_bf16 v[120:123], v[140:143], v[170:173], v[120:123]
	v_mfma_f32_16x16x32_bf16 v[116:119], v[132:135], v[178:181], v[116:119]
	v_mfma_f32_16x16x32_bf16 v[112:115], v[140:143], v[178:181], v[112:115]
	v_mfma_f32_16x16x32_bf16 v[108:111], v[132:135], v[186:189], v[108:111]
	v_mfma_f32_16x16x32_bf16 v[104:107], v[140:143], v[186:189], v[104:107]
	v_mfma_f32_16x16x32_bf16 v[100:103], v[132:135], v[194:197], v[100:103]
	v_mfma_f32_16x16x32_bf16 v[96:99], v[140:143], v[194:197], v[96:99]
	v_mfma_f32_16x16x32_bf16 v[124:127], v[136:139], v[174:177], v[124:127]
	v_mfma_f32_16x16x32_bf16 v[120:123], v[144:147], v[174:177], v[120:123]
	v_mfma_f32_16x16x32_bf16 v[116:119], v[136:139], v[182:185], v[116:119]
	v_mfma_f32_16x16x32_bf16 v[112:115], v[144:147], v[182:185], v[112:115]
	v_mfma_f32_16x16x32_bf16 v[108:111], v[136:139], v[190:193], v[108:111]
	v_mfma_f32_16x16x32_bf16 v[104:107], v[144:147], v[190:193], v[104:107]
	v_mfma_f32_16x16x32_bf16 v[100:103], v[136:139], v[198:201], v[100:103]
	v_mfma_f32_16x16x32_bf16 v[96:99], v[144:147], v[198:201], v[96:99]
	s_setprio 0
	s_setprio 1
	v_mfma_f32_16x16x32_bf16 v[92:95], v[154:157], v[170:173], v[92:95]
	v_mfma_f32_16x16x32_bf16 v[88:91], v[162:165], v[170:173], v[88:91]
	v_mfma_f32_16x16x32_bf16 v[84:87], v[154:157], v[178:181], v[84:87]
	v_mfma_f32_16x16x32_bf16 v[80:83], v[162:165], v[178:181], v[80:83]
	v_mfma_f32_16x16x32_bf16 v[76:79], v[154:157], v[186:189], v[76:79]
	v_mfma_f32_16x16x32_bf16 v[72:75], v[162:165], v[186:189], v[72:75]
	v_mfma_f32_16x16x32_bf16 v[68:71], v[154:157], v[194:197], v[68:71]
	v_mfma_f32_16x16x32_bf16 v[64:67], v[162:165], v[194:197], v[64:67]
	v_mfma_f32_16x16x32_bf16 v[92:95], v[158:161], v[174:177], v[92:95]
	v_mfma_f32_16x16x32_bf16 v[88:91], v[166:169], v[174:177], v[88:91]
	v_mfma_f32_16x16x32_bf16 v[84:87], v[158:161], v[182:185], v[84:87]
	v_mfma_f32_16x16x32_bf16 v[80:83], v[166:169], v[182:185], v[80:83]
	v_mfma_f32_16x16x32_bf16 v[76:79], v[158:161], v[190:193], v[76:79]
	v_mfma_f32_16x16x32_bf16 v[72:75], v[166:169], v[190:193], v[72:75]
	v_mfma_f32_16x16x32_bf16 v[68:71], v[158:161], v[198:201], v[68:71]
	v_mfma_f32_16x16x32_bf16 v[64:67], v[166:169], v[198:201], v[64:67]
	s_barrier
; #define PG8_STAGE(bufoff, gbase, voff) do { const __amdgpu_buffer_rsrc_t _rs = __builtin_amdgcn_make_buffer_rsrc((void*)(gbase), 0, 0x7fffffff, 0x00020000); _Pragma("unroll") for (int _i = 0; _i < 2; ++_i) \
;         __builtin_amdgcn_raw_ptr_buffer_load_lds(_rs, (LAS unsigned*)(lds + (bufoff) + ldsw + _i * 8192), 16, (int)(voff)[_i], 0, 0, 0); } while (0)
; #define PG8_WAIT_V(n) asm volatile("s_waitcnt vmcnt(" #n ")" ::: "memory")
; #define PG8_WAIT_L(n) asm volatile("s_waitcnt lgkmcnt(" #n ")" ::: "memory")
; #define PG8_BAR __builtin_amdgcn_s_barrier()
; #define PG8_SCHED __builtin_amdgcn_sched_barrier(0)
; template <class Epi, class Sched, bool F8 = false>
; __device__ __forceinline__ void gemm_phase(LAS unsigned char* lds, const int lda, const int ldb, const Sched& S, const Epi& E) {
;     ...
;             PG8_LDA(At, 1, 1); PG8_STAGE(PG8_SB(1, 0), b3, voffB); PG8_STAGE(PG8_SB(1, 1), b3 + hstepB, voffB); PG8_STAGE(PG8_SA(1, 0), a3, voffA);
;             PG8_WAIT_V(8); PG8_WAIT_L(0); PG8_BAR; PG8_MMA(1, 0, At, B0); PG8_MMA(1, 1, At, B1); PG8_BAR; PG8_SCHED;
	s_setprio 0
	s_add_u32 s4, s36, 0x8000
	s_addc_u32 s5, s18, 0
	s_mov_b32 m0, s85
	s_and_b32 s5, s5, 0xffff
	ds_read_b128 v[170:173], v153 offset:49152
	ds_read_b128 v[174:177], v153 offset:50176
	ds_read_b128 v[178:181], v153 offset:51200
	ds_read_b128 v[182:185], v153 offset:52224
	ds_read_b128 v[186:189], v153 offset:53248
	ds_read_b128 v[190:193], v153 offset:54272
	ds_read_b128 v[194:197], v153 offset:55296
	ds_read_b128 v[198:201], v153 offset:56320
	buffer_load_dwordx4 v149, s[4:7], 0 offen lds
	s_mov_b32 m0, s86
	s_mov_b32 s19, s7
	buffer_load_dwordx4 v151, s[4:7], 0 offen lds
	s_add_u32 s4, s36, 0xc000
	s_addc_u32 s5, s18, 0
	s_and_b32 s5, s5, 0xffff
	s_mov_b32 m0, s89
	s_and_b32 s17, s17, 0xffff
	buffer_load_dwordx4 v149, s[4:7], 0 offen lds
	s_mov_b32 m0, s90
	s_mov_b32 s18, s6
	buffer_load_dwordx4 v151, s[4:7], 0 offen lds
	s_mov_b32 m0, s87
	s_nop 0
	buffer_load_dwordx4 v148, s[16:19], 0 offen lds
	s_mov_b32 m0, s88
	s_nop 0
	buffer_load_dwordx4 v150, s[16:19], 0 offen lds
	s_waitcnt vmcnt(8)
	s_waitcnt lgkmcnt(0)
	s_setprio 1
	s_barrier
	v_mfma_f32_16x16x32_bf16 v[60:63], v[132:135], v[170:173], v[60:63]
	v_mfma_f32_16x16x32_bf16 v[56:59], v[140:143], v[170:173], v[56:59]
	v_mfma_f32_16x16x32_bf16 v[52:55], v[132:135], v[178:181], v[52:55]
	v_mfma_f32_16x16x32_bf16 v[48:51], v[140:143], v[178:181], v[48:51]
	v_mfma_f32_16x16x32_bf16 v[44:47], v[132:135], v[186:189], v[44:47]
	v_mfma_f32_16x16x32_bf16 v[40:43], v[140:143], v[186:189], v[40:43]
	v_mfma_f32_16x16x32_bf16 v[36:39], v[132:135], v[194:197], v[36:39]
	v_mfma_f32_16x16x32_bf16 v[32:35], v[140:143], v[194:197], v[32:35]
	v_mfma_f32_16x16x32_bf16 v[60:63], v[136:139], v[174:177], v[60:63]
	v_mfma_f32_16x16x32_bf16 v[56:59], v[144:147], v[174:177], v[56:59]
	v_mfma_f32_16x16x32_bf16 v[52:55], v[136:139], v[182:185], v[52:55]
	v_mfma_f32_16x16x32_bf16 v[48:51], v[144:147], v[182:185], v[48:51]
	v_mfma_f32_16x16x32_bf16 v[44:47], v[136:139], v[190:193], v[44:47]
	v_mfma_f32_16x16x32_bf16 v[40:43], v[144:147], v[190:193], v[40:43]
	v_mfma_f32_16x16x32_bf16 v[36:39], v[136:139], v[198:201], v[36:39]
	v_mfma_f32_16x16x32_bf16 v[32:35], v[144:147], v[198:201], v[32:35]
	s_setprio 0
	s_setprio 1
	v_mfma_f32_16x16x32_bf16 v[28:31], v[154:157], v[170:173], v[28:31]
	v_mfma_f32_16x16x32_bf16 v[24:27], v[162:165], v[170:173], v[24:27]
	v_mfma_f32_16x16x32_bf16 v[20:23], v[154:157], v[178:181], v[20:23]
	v_mfma_f32_16x16x32_bf16 v[16:19], v[162:165], v[178:181], v[16:19]
	v_mfma_f32_16x16x32_bf16 v[12:15], v[154:157], v[186:189], v[12:15]
	v_mfma_f32_16x16x32_bf16 v[8:11], v[162:165], v[186:189], v[8:11]
	v_mfma_f32_16x16x32_bf16 v[4:7], v[154:157], v[194:197], v[4:7]
	v_mfma_f32_16x16x32_bf16 v[0:3], v[162:165], v[194:197], v[0:3]
	v_mfma_f32_16x16x32_bf16 v[28:31], v[158:161], v[174:177], v[28:31]
	v_mfma_f32_16x16x32_bf16 v[24:27], v[166:169], v[174:177], v[24:27]
	v_mfma_f32_16x16x32_bf16 v[20:23], v[158:161], v[182:185], v[20:23]
	v_mfma_f32_16x16x32_bf16 v[16:19], v[166:169], v[182:185], v[16:19]
	v_mfma_f32_16x16x32_bf16 v[12:15], v[158:161], v[190:193], v[12:15]
	v_mfma_f32_16x16x32_bf16 v[8:11], v[166:169], v[190:193], v[8:11]
	v_mfma_f32_16x16x32_bf16 v[4:7], v[158:161], v[198:201], v[4:7]
	v_mfma_f32_16x16x32_bf16 v[0:3], v[166:169], v[198:201], v[0:3]
	s_barrier
	s_setprio 0
	s_add_i32 s63, s63, 2
	s_add_u32 s9, s9, 0x10000
	s_addc_u32 s33, s33, 0
	s_add_u32 s47, s47, 0x100
	s_addc_u32 s62, s62, 0
	s_cmp_gt_u32 s63, 29
	s_cbranch_scc0 .LBB0_485
	s_and_b64 vcc, exec, s[44:45]
	s_cbranch_vccz .LBB0_488
	s_barrier

; #define PG8_STAGE(bufoff, gbase, voff) do { const __amdgpu_buffer_rsrc_t _rs = __builtin_amdgcn_make_buffer_rsrc((void*)(gbase), 0, 0x7fffffff, 0x00020000); _Pragma("unroll") for (int _i = 0; _i < 2; ++_i) \
;         __builtin_amdgcn_raw_ptr_buffer_load_lds(_rs, (LAS unsigned*)(lds + (bufoff) + ldsw + _i * 8192), 16, (int)(voff)[_i], 0, 0, 0); } while (0)
; #define PG8_WAIT_V(n) asm volatile("s_waitcnt vmcnt(" #n ")" ::: "memory")
; #define PG8_WAIT_L(n) asm volatile("s_waitcnt lgkmcnt(" #n ")" ::: "memory")
; #define PG8_BAR __builtin_amdgcn_s_barrier()
; #define PG8_SCHED __builtin_amdgcn_sched_barrier(0)
; template <class Epi, class Sched, bool F8 = false>
; __device__ __forceinline__ void gemm_phase(LAS unsigned char* lds, const int lda, const int ldb, const Sched& S, const Epi& E) {
;     ...
;             const char* a1 = cA + (size_t)(t + 1) * kstep;
;             const char* a2 = last ? nA : cA + (size_t)(t + 2) * kstep; const char* b2 = last ? nB : cB + (size_t)(t + 2) * kstepB;
;             const char* a3 = a2 + kstep; const char* b3 = b2 + kstepB;
;     ...
;             PG8_LDB(B0, 0, 0); PG8_LDB(B1, 0, 1); PG8_SCHED; PG8_LDA(At, 0, 0); PG8_STAGE(PG8_SA(1, 1), a1 + hstepA, voffA);
;             PG8_WAIT_V(8); PG8_WAIT_L(0); PG8_BAR; PG8_MMA(0, 0, At, B0); PG8_MMA(0, 1, At, B1); PG8_BAR; PG8_SCHED;
;             PG8_LDA(At, 0, 1); PG8_STAGE(PG8_SB(0, 0), b2, voffB); PG8_STAGE(PG8_SB(0, 1), b2 + hstepB, voffB); PG8_STAGE(PG8_SA(0, 0), a2, voffA);
;             PG8_WAIT_V(8); PG8_WAIT_L(0); PG8_BAR; PG8_MMA(1, 0, At, B0); PG8_MMA(1, 1, At, B1); PG8_BAR; PG8_SCHED;
.LBB0_632:
	ds_read_b128 v[132:135], v142
	ds_read_b128 v[148:151], v142 offset:1024
	ds_read_b128 v[152:155], v142 offset:2048
	ds_read_b128 v[156:159], v142 offset:3072
	ds_read_b128 v[160:163], v143
	ds_read_b128 v[164:167], v143 offset:1024
	ds_read_b128 v[168:171], v143 offset:2048
	ds_read_b128 v[172:175], v143 offset:3072
	s_add_u32 s4, vcc_lo, 0xfff00080
	s_addc_u32 s5, vcc_hi, -1
	s_cmp_eq_u32 s64, 60
	s_cselect_b32 s40, s68, s4
	s_cselect_b32 s19, s69, s5
	s_cselect_b32 s18, s71, s67
	s_cselect_b32 s36, s70, s51
	s_add_u32 s16, s40, 0x80
	s_addc_u32 s17, s19, 0
	s_and_b32 s5, vcc_hi, 0xffff
	s_mov_b32 s4, vcc_lo
	s_mov_b32 m0, s92
	ds_read_b128 v[176:179], v144
	ds_read_b128 v[180:183], v144 offset:1024
	ds_read_b128 v[184:187], v144 offset:2048
	ds_read_b128 v[188:191], v144 offset:3072
	ds_read_b128 v[192:195], v144 offset:4096
	ds_read_b128 v[196:199], v144 offset:5120
	ds_read_b128 v[200:203], v144 offset:6144
	ds_read_b128 v[204:207], v144 offset:7168
	buffer_load_dwordx4 v138, s[4:7], 0 offen lds
	s_mov_b32 m0, s93
	s_nop 0
	buffer_load_dwordx4 v140, s[4:7], 0 offen lds
	s_waitcnt vmcnt(8)
	s_waitcnt lgkmcnt(0)
	s_setprio 1
	s_barrier
	v_mfma_f32_16x16x32_bf16 v[124:127], v[132:135], v[176:179], v[124:127]
	v_mfma_f32_16x16x32_bf16 v[120:123], v[152:155], v[176:179], v[120:123]
	v_mfma_f32_16x16x32_bf16 v[108:111], v[132:135], v[184:187], v[108:111]
	v_mfma_f32_16x16x32_bf16 v[104:107], v[152:155], v[184:187], v[104:107]
	v_mfma_f32_16x16x32_bf16 v[92:95], v[132:135], v[192:195], v[92:95]
	v_mfma_f32_16x16x32_bf16 v[88:91], v[152:155], v[192:195], v[88:91]
	v_mfma_f32_16x16x32_bf16 v[76:79], v[132:135], v[200:203], v[76:79]
	v_mfma_f32_16x16x32_bf16 v[72:75], v[152:155], v[200:203], v[72:75]
	v_mfma_f32_16x16x32_bf16 v[124:127], v[148:151], v[180:183], v[124:127]
	v_mfma_f32_16x16x32_bf16 v[120:123], v[156:159], v[180:183], v[120:123]
	v_mfma_f32_16x16x32_bf16 v[108:111], v[148:151], v[188:191], v[108:111]
	v_mfma_f32_16x16x32_bf16 v[104:107], v[156:159], v[188:191], v[104:107]
	v_mfma_f32_16x16x32_bf16 v[92:95], v[148:151], v[196:199], v[92:95]
	v_mfma_f32_16x16x32_bf16 v[88:91], v[156:159], v[196:199], v[88:91]
	v_mfma_f32_16x16x32_bf16 v[76:79], v[148:151], v[204:207], v[76:79]
	v_mfma_f32_16x16x32_bf16 v[72:75], v[156:159], v[204:207], v[72:75]
	s_setprio 0
	s_setprio 1
	v_mfma_f32_16x16x32_bf16 v[116:119], v[160:163], v[176:179], v[116:119]
	v_mfma_f32_16x16x32_bf16 v[112:115], v[168:171], v[176:179], v[112:115]
	v_mfma_f32_16x16x32_bf16 v[100:103], v[160:163], v[184:187], v[100:103]
	v_mfma_f32_16x16x32_bf16 v[96:99], v[168:171], v[184:187], v[96:99]
	v_mfma_f32_16x16x32_bf16 v[84:87], v[160:163], v[192:195], v[84:87]
	v_mfma_f32_16x16x32_bf16 v[80:83], v[168:171], v[192:195], v[80:83]
	v_mfma_f32_16x16x32_bf16 v[68:71], v[160:163], v[200:203], v[68:71]
	v_mfma_f32_16x16x32_bf16 v[64:67], v[168:171], v[200:203], v[64:67]
	v_mfma_f32_16x16x32_bf16 v[116:119], v[164:167], v[180:183], v[116:119]
	v_mfma_f32_16x16x32_bf16 v[112:115], v[172:175], v[180:183], v[112:115]
	v_mfma_f32_16x16x32_bf16 v[100:103], v[164:167], v[188:191], v[100:103]
	v_mfma_f32_16x16x32_bf16 v[96:99], v[172:175], v[188:191], v[96:99]
	v_mfma_f32_16x16x32_bf16 v[84:87], v[164:167], v[196:199], v[84:87]
	v_mfma_f32_16x16x32_bf16 v[80:83], v[172:175], v[196:199], v[80:83]
	v_mfma_f32_16x16x32_bf16 v[68:71], v[164:167], v[204:207], v[68:71]
	v_mfma_f32_16x16x32_bf16 v[64:67], v[172:175], v[204:207], v[64:67]
	s_barrier
	s_setprio 0
	s_and_b32 s37, s18, 0xffff
	s_mov_b32 m0, s73
	s_mov_b32 s38, s6
	s_mov_b32 s39, s7
	s_add_u32 s4, s36, 0x4000
	ds_read_b128 v[176:179], v144 offset:16384
	ds_read_b128 v[180:183], v144 offset:17408
	ds_read_b128 v[184:187], v144 offset:18432
	ds_read_b128 v[188:191], v144 offset:19456
	ds_read_b128 v[192:195], v144 offset:20480
	ds_read_b128 v[196:199], v144 offset:21504
	ds_read_b128 v[200:203], v144 offset:22528
	ds_read_b128 v[204:207], v144 offset:23552
	buffer_load_dwordx4 v139, s[36:39], 0 offen lds
	s_mov_b32 m0, s74
	s_addc_u32 s5, s18, 0
	buffer_load_dwordx4 v141, s[36:39], 0 offen lds
	s_and_b32 s5, s5, 0xffff
	s_mov_b32 m0, s75
	s_and_b32 s41, s19, 0xffff
	buffer_load_dwordx4 v139, s[4:7], 0 offen lds
	s_mov_b32 m0, s76
	s_mov_b32 s42, s6
	buffer_load_dwordx4 v141, s[4:7], 0 offen lds
	s_mov_b32 s43, s7
	s_mov_b32 m0, s61
	s_nop 0
	buffer_load_dwordx4 v138, s[40:43], 0 offen lds
	s_mov_b32 m0, s77
	s_nop 0
	buffer_load_dwordx4 v140, s[40:43], 0 offen lds
	s_waitcnt vmcnt(8)
	s_waitcnt lgkmcnt(0)
	s_setprio 1
	s_barrier
; #define PG8_STAGE(bufoff, gbase, voff) do { const __amdgpu_buffer_rsrc_t _rs = __builtin_amdgcn_make_buffer_rsrc((void*)(gbase), 0, 0x7fffffff, 0x00020000); _Pragma("unroll") for (int _i = 0; _i < 2; ++_i) \
;         __builtin_amdgcn_raw_ptr_buffer_load_lds(_rs, (LAS unsigned*)(lds + (bufoff) + ldsw + _i * 8192), 16, (int)(voff)[_i], 0, 0, 0); } while (0)
; #define PG8_WAIT_V(n) asm volatile("s_waitcnt vmcnt(" #n ")" ::: "memory")
; #define PG8_WAIT_L(n) asm volatile("s_waitcnt lgkmcnt(" #n ")" ::: "memory")
; #define PG8_BAR __builtin_amdgcn_s_barrier()
; #define PG8_SCHED __builtin_amdgcn_sched_barrier(0)
; template <class Epi, class Sched, bool F8 = false>
; __device__ __forceinline__ void gemm_phase(LAS unsigned char* lds, const int lda, const int ldb, const Sched& S, const Epi& E) {
;     ...
;             PG8_WAIT_V(8); PG8_WAIT_L(0); PG8_BAR; PG8_MMA(1, 0, At, B0); PG8_MMA(1, 1, At, B1); PG8_BAR; PG8_SCHED;
;             PG8_LDB(B0, 1, 0); PG8_LDB(B1, 1, 1); PG8_SCHED; PG8_LDA(At, 1, 0); PG8_STAGE(PG8_SA(0, 1), a2 + hstepA, voffA);
;             PG8_WAIT_V(8); PG8_WAIT_L(0); PG8_BAR; PG8_MMA(0, 0, At, B0); PG8_MMA(0, 1, At, B1); PG8_BAR; PG8_SCHED;
	v_mfma_f32_16x16x32_bf16 v[60:63], v[132:135], v[176:179], v[60:63]
	v_mfma_f32_16x16x32_bf16 v[56:59], v[152:155], v[176:179], v[56:59]
	v_mfma_f32_16x16x32_bf16 v[44:47], v[132:135], v[184:187], v[44:47]
	v_mfma_f32_16x16x32_bf16 v[40:43], v[152:155], v[184:187], v[40:43]
	v_mfma_f32_16x16x32_bf16 v[28:31], v[132:135], v[192:195], v[28:31]
	v_mfma_f32_16x16x32_bf16 v[24:27], v[152:155], v[192:195], v[24:27]
	v_mfma_f32_16x16x32_bf16 v[12:15], v[132:135], v[200:203], v[12:15]
	v_mfma_f32_16x16x32_bf16 v[8:11], v[152:155], v[200:203], v[8:11]
	v_mfma_f32_16x16x32_bf16 v[60:63], v[148:151], v[180:183], v[60:63]
	v_mfma_f32_16x16x32_bf16 v[56:59], v[156:159], v[180:183], v[56:59]
	v_mfma_f32_16x16x32_bf16 v[44:47], v[148:151], v[188:191], v[44:47]
	v_mfma_f32_16x16x32_bf16 v[40:43], v[156:159], v[188:191], v[40:43]
	v_mfma_f32_16x16x32_bf16 v[28:31], v[148:151], v[196:199], v[28:31]
	v_mfma_f32_16x16x32_bf16 v[24:27], v[156:159], v[196:199], v[24:27]
	v_mfma_f32_16x16x32_bf16 v[12:15], v[148:151], v[204:207], v[12:15]
	v_mfma_f32_16x16x32_bf16 v[8:11], v[156:159], v[204:207], v[8:11]
	s_setprio 0
	s_setprio 1
	v_mfma_f32_16x16x32_bf16 v[52:55], v[160:163], v[176:179], v[52:55]
	v_mfma_f32_16x16x32_bf16 v[48:51], v[168:171], v[176:179], v[48:51]
	v_mfma_f32_16x16x32_bf16 v[36:39], v[160:163], v[184:187], v[36:39]
	v_mfma_f32_16x16x32_bf16 v[32:35], v[168:171], v[184:187], v[32:35]
	v_mfma_f32_16x16x32_bf16 v[20:23], v[160:163], v[192:195], v[20:23]
	v_mfma_f32_16x16x32_bf16 v[16:19], v[168:171], v[192:195], v[16:19]
	v_mfma_f32_16x16x32_bf16 v[4:7], v[160:163], v[200:203], v[4:7]
	v_mfma_f32_16x16x32_bf16 v[0:3], v[168:171], v[200:203], v[0:3]
	v_mfma_f32_16x16x32_bf16 v[52:55], v[164:167], v[180:183], v[52:55]
	v_mfma_f32_16x16x32_bf16 v[48:51], v[172:175], v[180:183], v[48:51]
	v_mfma_f32_16x16x32_bf16 v[36:39], v[164:167], v[188:191], v[36:39]
	v_mfma_f32_16x16x32_bf16 v[32:35], v[172:175], v[188:191], v[32:35]
	v_mfma_f32_16x16x32_bf16 v[20:23], v[164:167], v[196:199], v[20:23]
	v_mfma_f32_16x16x32_bf16 v[16:19], v[172:175], v[196:199], v[16:19]
	v_mfma_f32_16x16x32_bf16 v[4:7], v[164:167], v[204:207], v[4:7]
	v_mfma_f32_16x16x32_bf16 v[0:3], v[172:175], v[204:207], v[0:3]
	s_barrier
	s_setprio 0
	ds_read_b128 v[132:135], v145
	ds_read_b128 v[148:151], v145 offset:1024
	ds_read_b128 v[152:155], v145 offset:2048
	ds_read_b128 v[156:159], v145 offset:3072
	ds_read_b128 v[160:163], v146
	ds_read_b128 v[164:167], v146 offset:1024
	ds_read_b128 v[168:171], v146 offset:2048
	ds_read_b128 v[172:175], v146 offset:3072
	s_add_u32 s4, s40, 0x100000
	s_addc_u32 s5, s19, 0
	s_and_b32 s5, s5, 0xffff
	s_mov_b32 m0, s78
	ds_read_b128 v[176:179], v144 offset:32768
	ds_read_b128 v[180:183], v144 offset:33792
	ds_read_b128 v[184:187], v144 offset:34816
	ds_read_b128 v[188:191], v144 offset:35840
	ds_read_b128 v[192:195], v144 offset:36864
	ds_read_b128 v[196:199], v144 offset:37888
	ds_read_b128 v[200:203], v144 offset:38912
	ds_read_b128 v[204:207], v144 offset:39936
	buffer_load_dwordx4 v138, s[4:7], 0 offen lds
	s_mov_b32 m0, s79
	s_nop 0
	buffer_load_dwordx4 v140, s[4:7], 0 offen lds
	s_waitcnt vmcnt(8)
	s_waitcnt lgkmcnt(0)
	s_setprio 1
	s_barrier
	v_mfma_f32_16x16x32_bf16 v[124:127], v[132:135], v[176:179], v[124:127]
	v_mfma_f32_16x16x32_bf16 v[120:123], v[152:155], v[176:179], v[120:123]
	v_mfma_f32_16x16x32_bf16 v[108:111], v[132:135], v[184:187], v[108:111]
	v_mfma_f32_16x16x32_bf16 v[104:107], v[152:155], v[184:187], v[104:107]
	v_mfma_f32_16x16x32_bf16 v[92:95], v[132:135], v[192:195], v[92:95]
	v_mfma_f32_16x16x32_bf16 v[88:91], v[152:155], v[192:195], v[88:91]
	v_mfma_f32_16x16x32_bf16 v[76:79], v[132:135], v[200:203], v[76:79]
	v_mfma_f32_16x16x32_bf16 v[72:75], v[152:155], v[200:203], v[72:75]
	v_mfma_f32_16x16x32_bf16 v[124:127], v[148:151], v[180:183], v[124:127]
	v_mfma_f32_16x16x32_bf16 v[120:123], v[156:159], v[180:183], v[120:123]
	v_mfma_f32_16x16x32_bf16 v[108:111], v[148:151], v[188:191], v[108:111]
	v_mfma_f32_16x16x32_bf16 v[104:107], v[156:159], v[188:191], v[104:107]
	v_mfma_f32_16x16x32_bf16 v[92:95], v[148:151], v[196:199], v[92:95]
	v_mfma_f32_16x16x32_bf16 v[88:91], v[156:159], v[196:199], v[88:91]
	v_mfma_f32_16x16x32_bf16 v[76:79], v[148:151], v[204:207], v[76:79]
	v_mfma_f32_16x16x32_bf16 v[72:75], v[156:159], v[204:207], v[72:75]
	s_setprio 0
	s_setprio 1
	v_mfma_f32_16x16x32_bf16 v[116:119], v[160:163], v[176:179], v[116:119]
	v_mfma_f32_16x16x32_bf16 v[112:115], v[168:171], v[176:179], v[112:115]
	v_mfma_f32_16x16x32_bf16 v[100:103], v[160:163], v[184:187], v[100:103]
	v_mfma_f32_16x16x32_bf16 v[96:99], v[168:171], v[184:187], v[96:99]
	v_mfma_f32_16x16x32_bf16 v[84:87], v[160:163], v[192:195], v[84:87]
	v_mfma_f32_16x16x32_bf16 v[80:83], v[168:171], v[192:195], v[80:83]
	v_mfma_f32_16x16x32_bf16 v[68:71], v[160:163], v[200:203], v[68:71]
	v_mfma_f32_16x16x32_bf16 v[64:67], v[168:171], v[200:203], v[64:67]
	v_mfma_f32_16x16x32_bf16 v[116:119], v[164:167], v[180:183], v[116:119]
	v_mfma_f32_16x16x32_bf16 v[112:115], v[172:175], v[180:183], v[112:115]
	v_mfma_f32_16x16x32_bf16 v[100:103], v[164:167], v[188:191], v[100:103]
	v_mfma_f32_16x16x32_bf16 v[96:99], v[172:175], v[188:191], v[96:99]
	v_mfma_f32_16x16x32_bf16 v[84:87], v[164:167], v[196:199], v[84:87]
	v_mfma_f32_16x16x32_bf16 v[80:83], v[172:175], v[196:199], v[80:83]
	v_mfma_f32_16x16x32_bf16 v[68:71], v[164:167], v[204:207], v[68:71]
	v_mfma_f32_16x16x32_bf16 v[64:67], v[172:175], v[204:207], v[64:67]
	s_barrier
; #define PG8_STAGE(bufoff, gbase, voff) do { const __amdgpu_buffer_rsrc_t _rs = __builtin_amdgcn_make_buffer_rsrc((void*)(gbase), 0, 0x7fffffff, 0x00020000); _Pragma("unroll") for (int _i = 0; _i < 2; ++_i) \
;         __builtin_amdgcn_raw_ptr_buffer_load_lds(_rs, (LAS unsigned*)(lds + (bufoff) + ldsw + _i * 8192), 16, (int)(voff)[_i], 0, 0, 0); } while (0)
; #define PG8_WAIT_V(n) asm volatile("s_waitcnt vmcnt(" #n ")" ::: "memory")
; #define PG8_WAIT_L(n) asm volatile("s_waitcnt lgkmcnt(" #n ")" ::: "memory")
; #define PG8_BAR __builtin_amdgcn_s_barrier()
; #define PG8_SCHED __builtin_amdgcn_sched_barrier(0)
; template <class Epi, class Sched, bool F8 = false>
; __device__ __forceinline__ void gemm_phase(LAS unsigned char* lds, const int lda, const int ldb, const Sched& S, const Epi& E) {
;     ...
;             PG8_LDA(At, 1, 1); PG8_STAGE(PG8_SB(1, 0), b3, voffB); PG8_STAGE(PG8_SB(1, 1), b3 + hstepB, voffB); PG8_STAGE(PG8_SA(1, 0), a3, voffA);
;             PG8_WAIT_V(8); PG8_WAIT_L(0); PG8_BAR; PG8_MMA(1, 0, At, B0); PG8_MMA(1, 1, At, B1); PG8_BAR; PG8_SCHED;
	s_setprio 0
	s_add_u32 s4, s36, 0x8000
	s_addc_u32 s5, s18, 0
	s_mov_b32 m0, s86
	s_and_b32 s5, s5, 0xffff
	ds_read_b128 v[176:179], v144 offset:49152
	ds_read_b128 v[180:183], v144 offset:50176
	ds_read_b128 v[184:187], v144 offset:51200
	ds_read_b128 v[188:191], v144 offset:52224
	ds_read_b128 v[192:195], v144 offset:53248
	ds_read_b128 v[196:199], v144 offset:54272
	ds_read_b128 v[200:203], v144 offset:55296
	ds_read_b128 v[204:207], v144 offset:56320
	buffer_load_dwordx4 v139, s[4:7], 0 offen lds
	s_mov_b32 m0, s87
	s_mov_b32 s19, s7
	buffer_load_dwordx4 v141, s[4:7], 0 offen lds
	s_add_u32 s4, s36, 0xc000
	s_addc_u32 s5, s18, 0
	s_and_b32 s5, s5, 0xffff
	s_mov_b32 m0, s90
	s_and_b32 s17, s17, 0xffff
	buffer_load_dwordx4 v139, s[4:7], 0 offen lds
	s_mov_b32 m0, s91
	s_mov_b32 s18, s6
	buffer_load_dwordx4 v141, s[4:7], 0 offen lds
	s_mov_b32 m0, s88
	s_nop 0
	buffer_load_dwordx4 v138, s[16:19], 0 offen lds
	s_mov_b32 m0, s89
	s_nop 0
	buffer_load_dwordx4 v140, s[16:19], 0 offen lds
	s_waitcnt vmcnt(8)
	s_waitcnt lgkmcnt(0)
	s_setprio 1
	s_barrier
	v_mfma_f32_16x16x32_bf16 v[60:63], v[132:135], v[176:179], v[60:63]
	v_mfma_f32_16x16x32_bf16 v[56:59], v[152:155], v[176:179], v[56:59]
	v_mfma_f32_16x16x32_bf16 v[44:47], v[132:135], v[184:187], v[44:47]
	v_mfma_f32_16x16x32_bf16 v[40:43], v[152:155], v[184:187], v[40:43]
	v_mfma_f32_16x16x32_bf16 v[28:31], v[132:135], v[192:195], v[28:31]
	v_mfma_f32_16x16x32_bf16 v[24:27], v[152:155], v[192:195], v[24:27]
	v_mfma_f32_16x16x32_bf16 v[12:15], v[132:135], v[200:203], v[12:15]
	v_mfma_f32_16x16x32_bf16 v[8:11], v[152:155], v[200:203], v[8:11]
	v_mfma_f32_16x16x32_bf16 v[60:63], v[148:151], v[180:183], v[60:63]
	v_mfma_f32_16x16x32_bf16 v[56:59], v[156:159], v[180:183], v[56:59]
	v_mfma_f32_16x16x32_bf16 v[44:47], v[148:151], v[188:191], v[44:47]
	v_mfma_f32_16x16x32_bf16 v[40:43], v[156:159], v[188:191], v[40:43]
	v_mfma_f32_16x16x32_bf16 v[28:31], v[148:151], v[196:199], v[28:31]
	v_mfma_f32_16x16x32_bf16 v[24:27], v[156:159], v[196:199], v[24:27]
	v_mfma_f32_16x16x32_bf16 v[12:15], v[148:151], v[204:207], v[12:15]
	v_mfma_f32_16x16x32_bf16 v[8:11], v[156:159], v[204:207], v[8:11]
	s_setprio 0
	s_setprio 1
	v_mfma_f32_16x16x32_bf16 v[52:55], v[160:163], v[176:179], v[52:55]
	v_mfma_f32_16x16x32_bf16 v[48:51], v[168:171], v[176:179], v[48:51]
	v_mfma_f32_16x16x32_bf16 v[36:39], v[160:163], v[184:187], v[36:39]
	v_mfma_f32_16x16x32_bf16 v[32:35], v[168:171], v[184:187], v[32:35]
	v_mfma_f32_16x16x32_bf16 v[20:23], v[160:163], v[192:195], v[20:23]
	v_mfma_f32_16x16x32_bf16 v[16:19], v[168:171], v[192:195], v[16:19]
	v_mfma_f32_16x16x32_bf16 v[4:7], v[160:163], v[200:203], v[4:7]
	v_mfma_f32_16x16x32_bf16 v[0:3], v[168:171], v[200:203], v[0:3]
	v_mfma_f32_16x16x32_bf16 v[52:55], v[164:167], v[180:183], v[52:55]
	v_mfma_f32_16x16x32_bf16 v[48:51], v[172:175], v[180:183], v[48:51]
	v_mfma_f32_16x16x32_bf16 v[36:39], v[164:167], v[188:191], v[36:39]
	v_mfma_f32_16x16x32_bf16 v[32:35], v[172:175], v[188:191], v[32:35]
	v_mfma_f32_16x16x32_bf16 v[20:23], v[164:167], v[196:199], v[20:23]
	v_mfma_f32_16x16x32_bf16 v[16:19], v[172:175], v[196:199], v[16:19]
	v_mfma_f32_16x16x32_bf16 v[4:7], v[164:167], v[204:207], v[4:7]
	v_mfma_f32_16x16x32_bf16 v[0:3], v[172:175], v[204:207], v[0:3]
	s_barrier
	s_setprio 0
	s_add_i32 s64, s64, 2
	s_add_u32 s51, s51, 0x10000
	s_addc_u32 s67, s67, 0
	s_add_u32 vcc_lo, vcc_lo, 0x100
	s_addc_u32 vcc_hi, vcc_hi, 0
	s_cmp_gt_u32 s64, 61
	s_cbranch_scc0 .LBB0_632
	s_and_b64 vcc, exec, s[26:27]
	s_cbranch_vccz .LBB0_635
	s_barrier

; #define PG8_STAGE(bufoff, gbase, voff) do { const __amdgpu_buffer_rsrc_t _rs = __builtin_amdgcn_make_buffer_rsrc((void*)(gbase), 0, 0x7fffffff, 0x00020000); _Pragma("unroll") for (int _i = 0; _i < 2; ++_i) \
;         __builtin_amdgcn_raw_ptr_buffer_load_lds(_rs, (LAS unsigned*)(lds + (bufoff) + ldsw + _i * 8192), 16, (int)(voff)[_i], 0, 0, 0); } while (0)
; #define PG8_WAIT_V(n) asm volatile("s_waitcnt vmcnt(" #n ")" ::: "memory")
; #define PG8_WAIT_L(n) asm volatile("s_waitcnt lgkmcnt(" #n ")" ::: "memory")
; #define PG8_BAR __builtin_amdgcn_s_barrier()
; #define PG8_SCHED __builtin_amdgcn_sched_barrier(0)
; template <class Epi, class Sched, bool F8 = false>
; __device__ __forceinline__ void gemm_phase(LAS unsigned char* lds, const int lda, const int ldb, const Sched& S, const Epi& E) {
;     ...
;             const char* a1 = cA + (size_t)(t + 1) * kstep;
;             const char* a2 = last ? nA : cA + (size_t)(t + 2) * kstep; const char* b2 = last ? nB : cB + (size_t)(t + 2) * kstepB;
;             const char* a3 = a2 + kstep; const char* b3 = b2 + kstepB;
;     ...
;             PG8_LDB(B0, 0, 0); PG8_LDB(B1, 0, 1); PG8_SCHED; PG8_LDA(At, 0, 0); PG8_STAGE(PG8_SA(1, 1), a1 + hstepA, voffA);
;             PG8_WAIT_V(8); PG8_WAIT_L(0); PG8_BAR; PG8_MMA(0, 0, At, B0); PG8_MMA(0, 1, At, B1); PG8_BAR; PG8_SCHED;
;             PG8_LDA(At, 0, 1); PG8_STAGE(PG8_SB(0, 0), b2, voffB); PG8_STAGE(PG8_SB(0, 1), b2 + hstepB, voffB); PG8_STAGE(PG8_SA(0, 0), a2, voffA);
;             PG8_WAIT_V(8); PG8_WAIT_L(0); PG8_BAR; PG8_MMA(1, 0, At, B0); PG8_MMA(1, 1, At, B1); PG8_BAR; PG8_SCHED;
.LBB0_778:
	ds_read_b128 v[118:121], v194
	ds_read_b128 v[122:125], v194 offset:1024
	ds_read_b128 v[130:133], v194 offset:2048
	ds_read_b128 v[134:137], v194 offset:3072
	ds_read_b128 v[138:141], v195
	ds_read_b128 v[142:145], v195 offset:1024
	ds_read_b128 v[146:149], v195 offset:2048
	ds_read_b128 v[150:153], v195 offset:3072
	s_add_u32 s4, s33, 0xfff00080
	s_addc_u32 s5, s43, -1
	s_cmp_eq_u32 s45, 60
	s_cselect_b32 s20, s46, s4
	s_cselect_b32 s7, s47, s5
	s_cselect_b32 s6, s49, s9
	s_cselect_b32 s16, s48, s8
	s_add_u32 s4, s20, 0x80
	s_addc_u32 s5, s7, 0
	s_and_b32 s13, s43, 0xffff
	s_mov_b32 s12, s33
	s_mov_b32 m0, s84
	ds_read_b128 v[162:165], v196
	ds_read_b128 v[166:169], v196 offset:1024
	ds_read_b128 v[170:173], v196 offset:2048
	ds_read_b128 v[186:189], v196 offset:3072
	ds_read_b128 v[200:203], v196 offset:4096
	ds_read_b128 v[204:207], v196 offset:5120
	ds_read_b128 v[208:211], v196 offset:6144
	ds_read_b128 v[212:215], v196 offset:7168
	buffer_load_dwordx4 v175, s[12:15], 0 offen lds
	s_mov_b32 m0, s86
	s_nop 0
	buffer_load_dwordx4 v179, s[12:15], 0 offen lds
	s_waitcnt vmcnt(8)
	s_waitcnt lgkmcnt(0)
	s_setprio 1
	s_barrier
	v_mfma_f32_16x16x32_bf16 v[158:161], v[118:121], v[162:165], v[158:161]
	v_mfma_f32_16x16x32_bf16 v[60:63], v[130:133], v[162:165], v[60:63]
	v_mfma_f32_16x16x32_bf16 v[154:157], v[118:121], v[170:173], v[154:157]
	v_mfma_f32_16x16x32_bf16 v[52:55], v[130:133], v[170:173], v[52:55]
	v_mfma_f32_16x16x32_bf16 v[114:117], v[118:121], v[200:203], v[114:117]
	v_mfma_f32_16x16x32_bf16 v[44:47], v[130:133], v[200:203], v[44:47]
	v_mfma_f32_16x16x32_bf16 v[108:111], v[118:121], v[208:211], v[110:113]
	v_mfma_f32_16x16x32_bf16 v[36:39], v[130:133], v[208:211], v[36:39]
	v_mfma_f32_16x16x32_bf16 v[158:161], v[122:125], v[166:169], v[158:161]
	v_mfma_f32_16x16x32_bf16 v[60:63], v[134:137], v[166:169], v[60:63]
	v_mfma_f32_16x16x32_bf16 v[154:157], v[122:125], v[186:189], v[154:157]
	v_mfma_f32_16x16x32_bf16 v[52:55], v[134:137], v[186:189], v[52:55]
	v_mfma_f32_16x16x32_bf16 v[114:117], v[122:125], v[204:207], v[114:117]
	v_mfma_f32_16x16x32_bf16 v[44:47], v[134:137], v[204:207], v[44:47]
	v_mfma_f32_16x16x32_bf16 v[108:111], v[122:125], v[212:215], v[108:111]
	v_mfma_f32_16x16x32_bf16 v[36:39], v[134:137], v[212:215], v[36:39]
	s_setprio 0
	s_setprio 1
	v_mfma_f32_16x16x32_bf16 v[104:107], v[138:141], v[162:165], v[104:107]
	v_mfma_f32_16x16x32_bf16 v[56:59], v[146:149], v[162:165], v[56:59]
	v_mfma_f32_16x16x32_bf16 v[126:129], v[138:141], v[170:173], v[126:129]
	v_mfma_f32_16x16x32_bf16 v[48:51], v[146:149], v[170:173], v[48:51]
	v_mfma_f32_16x16x32_bf16 v[100:103], v[138:141], v[200:203], v[100:103]
	v_mfma_f32_16x16x32_bf16 v[40:43], v[146:149], v[200:203], v[40:43]
	v_mfma_f32_16x16x32_bf16 v[96:99], v[138:141], v[208:211], v[96:99]
	v_mfma_f32_16x16x32_bf16 v[32:35], v[146:149], v[208:211], v[32:35]
	v_mfma_f32_16x16x32_bf16 v[104:107], v[142:145], v[166:169], v[104:107]
	v_mfma_f32_16x16x32_bf16 v[56:59], v[150:153], v[166:169], v[56:59]
	v_mfma_f32_16x16x32_bf16 v[126:129], v[142:145], v[186:189], v[126:129]
	v_mfma_f32_16x16x32_bf16 v[48:51], v[150:153], v[186:189], v[48:51]
	v_mfma_f32_16x16x32_bf16 v[100:103], v[142:145], v[204:207], v[100:103]
	v_mfma_f32_16x16x32_bf16 v[40:43], v[150:153], v[204:207], v[40:43]
	v_mfma_f32_16x16x32_bf16 v[96:99], v[142:145], v[212:215], v[96:99]
	v_mfma_f32_16x16x32_bf16 v[32:35], v[150:153], v[212:215], v[32:35]
	s_barrier
	s_setprio 0
	s_and_b32 s17, s6, 0xffff
	s_mov_b32 m0, s68
	s_mov_b32 s18, s14
	s_mov_b32 s19, s15
	s_add_u32 s12, s16, 0x4000
	ds_read_b128 v[162:165], v196 offset:16384
	ds_read_b128 v[166:169], v196 offset:17408
	ds_read_b128 v[170:173], v196 offset:18432
	ds_read_b128 v[186:189], v196 offset:19456
	ds_read_b128 v[200:203], v196 offset:20480
	ds_read_b128 v[204:207], v196 offset:21504
	ds_read_b128 v[208:211], v196 offset:22528
	ds_read_b128 v[212:215], v196 offset:23552
	buffer_load_dwordx4 v177, s[16:19], 0 offen lds
	s_mov_b32 m0, s69
	s_addc_u32 s13, s6, 0
	buffer_load_dwordx4 v193, s[16:19], 0 offen lds
	s_and_b32 s13, s13, 0xffff
	s_mov_b32 m0, s70
	s_and_b32 s21, s7, 0xffff
	buffer_load_dwordx4 v177, s[12:15], 0 offen lds
	s_mov_b32 m0, s71
	s_mov_b32 s22, s14
	buffer_load_dwordx4 v193, s[12:15], 0 offen lds
	s_mov_b32 s23, s15
	s_mov_b32 m0, s51
	s_nop 0
	buffer_load_dwordx4 v175, s[20:23], 0 offen lds
	s_mov_b32 m0, s72
	s_nop 0
	buffer_load_dwordx4 v179, s[20:23], 0 offen lds
	s_waitcnt vmcnt(8)
	s_waitcnt lgkmcnt(0)
	s_setprio 1
	s_barrier
	v_mfma_f32_16x16x32_bf16 v[92:95], v[118:121], v[162:165], v[92:95]
	v_mfma_f32_16x16x32_bf16 v[28:31], v[130:133], v[162:165], v[28:31]
	v_mfma_f32_16x16x32_bf16 v[84:87], v[118:121], v[170:173], v[84:87]
	v_mfma_f32_16x16x32_bf16 v[20:23], v[130:133], v[170:173], v[20:23]
	v_mfma_f32_16x16x32_bf16 v[76:79], v[118:121], v[200:203], v[76:79]
	v_mfma_f32_16x16x32_bf16 v[12:15], v[130:133], v[200:203], v[12:15]
	v_mfma_f32_16x16x32_bf16 v[72:75], v[118:121], v[208:211], v[72:75]
	v_mfma_f32_16x16x32_bf16 v[4:7], v[130:133], v[208:211], v[4:7]
	v_mfma_f32_16x16x32_bf16 v[92:95], v[122:125], v[166:169], v[92:95]
	v_mfma_f32_16x16x32_bf16 v[28:31], v[134:137], v[166:169], v[28:31]
	v_mfma_f32_16x16x32_bf16 v[84:87], v[122:125], v[186:189], v[84:87]
	v_mfma_f32_16x16x32_bf16 v[20:23], v[134:137], v[186:189], v[20:23]
	v_mfma_f32_16x16x32_bf16 v[76:79], v[122:125], v[204:207], v[76:79]
	v_mfma_f32_16x16x32_bf16 v[12:15], v[134:137], v[204:207], v[12:15]
	v_mfma_f32_16x16x32_bf16 v[72:75], v[122:125], v[212:215], v[72:75]
	v_mfma_f32_16x16x32_bf16 v[4:7], v[134:137], v[212:215], v[4:7]
	s_setprio 0
	s_setprio 1
	v_mfma_f32_16x16x32_bf16 v[88:91], v[138:141], v[162:165], v[88:91]
	v_mfma_f32_16x16x32_bf16 v[24:27], v[146:149], v[162:165], v[24:27]
	v_mfma_f32_16x16x32_bf16 v[80:83], v[138:141], v[170:173], v[80:83]
	v_mfma_f32_16x16x32_bf16 v[16:19], v[146:149], v[170:173], v[16:19]
	v_mfma_f32_16x16x32_bf16 v[68:71], v[138:141], v[200:203], v[68:71]
	v_mfma_f32_16x16x32_bf16 v[8:11], v[146:149], v[200:203], v[8:11]
	v_mfma_f32_16x16x32_bf16 v[64:67], v[138:141], v[208:211], v[64:67]
	v_mfma_f32_16x16x32_bf16 v[0:3], v[146:149], v[208:211], v[0:3]
	v_mfma_f32_16x16x32_bf16 v[88:91], v[142:145], v[166:169], v[88:91]
	v_mfma_f32_16x16x32_bf16 v[24:27], v[150:153], v[166:169], v[24:27]
	v_mfma_f32_16x16x32_bf16 v[80:83], v[142:145], v[186:189], v[80:83]
	v_mfma_f32_16x16x32_bf16 v[16:19], v[150:153], v[186:189], v[16:19]
	v_mfma_f32_16x16x32_bf16 v[68:71], v[142:145], v[204:207], v[68:71]
	v_mfma_f32_16x16x32_bf16 v[8:11], v[150:153], v[204:207], v[8:11]
	v_mfma_f32_16x16x32_bf16 v[64:67], v[142:145], v[212:215], v[64:67]
	v_mfma_f32_16x16x32_bf16 v[0:3], v[150:153], v[212:215], v[0:3]
	s_barrier
; #define PG8_STAGE(bufoff, gbase, voff) do { const __amdgpu_buffer_rsrc_t _rs = __builtin_amdgcn_make_buffer_rsrc((void*)(gbase), 0, 0x7fffffff, 0x00020000); _Pragma("unroll") for (int _i = 0; _i < 2; ++_i) \
;         __builtin_amdgcn_raw_ptr_buffer_load_lds(_rs, (LAS unsigned*)(lds + (bufoff) + ldsw + _i * 8192), 16, (int)(voff)[_i], 0, 0, 0); } while (0)
; #define PG8_WAIT_V(n) asm volatile("s_waitcnt vmcnt(" #n ")" ::: "memory")
; #define PG8_WAIT_L(n) asm volatile("s_waitcnt lgkmcnt(" #n ")" ::: "memory")
; #define PG8_BAR __builtin_amdgcn_s_barrier()
; #define PG8_SCHED __builtin_amdgcn_sched_barrier(0)
; template <class Epi, class Sched, bool F8 = false>
; __device__ __forceinline__ void gemm_phase(LAS unsigned char* lds, const int lda, const int ldb, const Sched& S, const Epi& E) {
;     ...
;             PG8_LDB(B0, 1, 0); PG8_LDB(B1, 1, 1); PG8_SCHED; PG8_LDA(At, 1, 0); PG8_STAGE(PG8_SA(0, 1), a2 + hstepA, voffA);
;             PG8_WAIT_V(8); PG8_WAIT_L(0); PG8_BAR; PG8_MMA(0, 0, At, B0); PG8_MMA(0, 1, At, B1); PG8_BAR; PG8_SCHED;
;             PG8_LDA(At, 1, 1); PG8_STAGE(PG8_SB(1, 0), b3, voffB); PG8_STAGE(PG8_SB(1, 1), b3 + hstepB, voffB); PG8_STAGE(PG8_SA(1, 0), a3, voffA);
;             PG8_WAIT_V(8); PG8_WAIT_L(0); PG8_BAR; PG8_MMA(1, 0, At, B0); PG8_MMA(1, 1, At, B1); PG8_BAR; PG8_SCHED;
	s_setprio 0
	ds_read_b128 v[118:121], v197
	ds_read_b128 v[122:125], v197 offset:1024
	ds_read_b128 v[130:133], v197 offset:2048
	ds_read_b128 v[134:137], v197 offset:3072
	ds_read_b128 v[138:141], v198
	ds_read_b128 v[142:145], v198 offset:1024
	ds_read_b128 v[146:149], v198 offset:2048
	ds_read_b128 v[150:153], v198 offset:3072
	s_add_u32 s12, s20, 0x100000
	s_addc_u32 s7, s7, 0
	s_and_b32 s13, s7, 0xffff
	s_mov_b32 m0, s73
	ds_read_b128 v[162:165], v196 offset:32768
	ds_read_b128 v[166:169], v196 offset:33792
	ds_read_b128 v[170:173], v196 offset:34816
	ds_read_b128 v[186:189], v196 offset:35840
	ds_read_b128 v[200:203], v196 offset:36864
	ds_read_b128 v[204:207], v196 offset:37888
	ds_read_b128 v[208:211], v196 offset:38912
	ds_read_b128 v[212:215], v196 offset:39936
	buffer_load_dwordx4 v175, s[12:15], 0 offen lds
	s_mov_b32 m0, s74
	s_nop 0
	buffer_load_dwordx4 v179, s[12:15], 0 offen lds
	s_waitcnt vmcnt(8)
	s_waitcnt lgkmcnt(0)
	s_setprio 1
	s_barrier
	v_mfma_f32_16x16x32_bf16 v[158:161], v[118:121], v[162:165], v[158:161]
	v_mfma_f32_16x16x32_bf16 v[60:63], v[130:133], v[162:165], v[60:63]
	v_mfma_f32_16x16x32_bf16 v[154:157], v[118:121], v[170:173], v[154:157]
	v_mfma_f32_16x16x32_bf16 v[52:55], v[130:133], v[170:173], v[52:55]
	v_mfma_f32_16x16x32_bf16 v[112:115], v[118:121], v[200:203], v[114:117]
	v_mfma_f32_16x16x32_bf16 v[44:47], v[130:133], v[200:203], v[44:47]
	v_mfma_f32_16x16x32_bf16 v[108:111], v[118:121], v[208:211], v[108:111]
	v_mfma_f32_16x16x32_bf16 v[36:39], v[130:133], v[208:211], v[36:39]
	v_mfma_f32_16x16x32_bf16 v[158:161], v[122:125], v[166:169], v[158:161]
	v_mfma_f32_16x16x32_bf16 v[60:63], v[134:137], v[166:169], v[60:63]
	v_mfma_f32_16x16x32_bf16 v[154:157], v[122:125], v[186:189], v[154:157]
	v_mfma_f32_16x16x32_bf16 v[52:55], v[134:137], v[186:189], v[52:55]
	v_mfma_f32_16x16x32_bf16 v[114:117], v[122:125], v[204:207], v[112:115]
	v_mfma_f32_16x16x32_bf16 v[44:47], v[134:137], v[204:207], v[44:47]
	v_mfma_f32_16x16x32_bf16 v[110:113], v[122:125], v[212:215], v[108:111]
	v_mfma_f32_16x16x32_bf16 v[36:39], v[134:137], v[212:215], v[36:39]
	s_setprio 0
	s_setprio 1
	v_mfma_f32_16x16x32_bf16 v[104:107], v[138:141], v[162:165], v[104:107]
	v_mfma_f32_16x16x32_bf16 v[56:59], v[146:149], v[162:165], v[56:59]
	v_mfma_f32_16x16x32_bf16 v[126:129], v[138:141], v[170:173], v[126:129]
	v_mfma_f32_16x16x32_bf16 v[48:51], v[146:149], v[170:173], v[48:51]
	v_mfma_f32_16x16x32_bf16 v[100:103], v[138:141], v[200:203], v[100:103]
	v_mfma_f32_16x16x32_bf16 v[40:43], v[146:149], v[200:203], v[40:43]
	v_mfma_f32_16x16x32_bf16 v[96:99], v[138:141], v[208:211], v[96:99]
	v_mfma_f32_16x16x32_bf16 v[32:35], v[146:149], v[208:211], v[32:35]
	v_mfma_f32_16x16x32_bf16 v[104:107], v[142:145], v[166:169], v[104:107]
	v_mfma_f32_16x16x32_bf16 v[56:59], v[150:153], v[166:169], v[56:59]
	v_mfma_f32_16x16x32_bf16 v[126:129], v[142:145], v[186:189], v[126:129]
	v_mfma_f32_16x16x32_bf16 v[48:51], v[150:153], v[186:189], v[48:51]
	v_mfma_f32_16x16x32_bf16 v[100:103], v[142:145], v[204:207], v[100:103]
	v_mfma_f32_16x16x32_bf16 v[40:43], v[150:153], v[204:207], v[40:43]
	v_mfma_f32_16x16x32_bf16 v[96:99], v[142:145], v[212:215], v[96:99]
	v_mfma_f32_16x16x32_bf16 v[32:35], v[150:153], v[212:215], v[32:35]
	s_barrier
	s_setprio 0
	s_add_u32 s12, s16, 0x8000
	s_addc_u32 s7, s6, 0
	s_mov_b32 m0, s78
	s_and_b32 s13, s7, 0xffff
	ds_read_b128 v[162:165], v196 offset:49152
	ds_read_b128 v[166:169], v196 offset:50176
	ds_read_b128 v[170:173], v196 offset:51200
	ds_read_b128 v[186:189], v196 offset:52224
	ds_read_b128 v[200:203], v196 offset:53248
	ds_read_b128 v[204:207], v196 offset:54272
	ds_read_b128 v[208:211], v196 offset:55296
	ds_read_b128 v[212:215], v196 offset:56320
	buffer_load_dwordx4 v177, s[12:15], 0 offen lds
	s_mov_b32 m0, s79
	s_mov_b32 s7, s15
	buffer_load_dwordx4 v193, s[12:15], 0 offen lds
	s_add_u32 s12, s16, 0xc000
	s_addc_u32 s6, s6, 0
	s_and_b32 s13, s6, 0xffff
	s_mov_b32 m0, s82
	s_and_b32 s5, s5, 0xffff
	buffer_load_dwordx4 v177, s[12:15], 0 offen lds
	s_mov_b32 m0, s83
	s_mov_b32 s6, s14
	buffer_load_dwordx4 v193, s[12:15], 0 offen lds
	s_mov_b32 m0, s80
	s_nop 0
	buffer_load_dwordx4 v175, s[4:7], 0 offen lds
	s_mov_b32 m0, s81
	s_nop 0
	buffer_load_dwordx4 v179, s[4:7], 0 offen lds
	s_waitcnt vmcnt(8)
	s_waitcnt lgkmcnt(0)
	s_setprio 1
	s_barrier
	v_mfma_f32_16x16x32_bf16 v[92:95], v[118:121], v[162:165], v[92:95]
	v_mfma_f32_16x16x32_bf16 v[28:31], v[130:133], v[162:165], v[28:31]
	v_mfma_f32_16x16x32_bf16 v[84:87], v[118:121], v[170:173], v[84:87]
	v_mfma_f32_16x16x32_bf16 v[20:23], v[130:133], v[170:173], v[20:23]
	v_mfma_f32_16x16x32_bf16 v[76:79], v[118:121], v[200:203], v[76:79]
	v_mfma_f32_16x16x32_bf16 v[12:15], v[130:133], v[200:203], v[12:15]
	v_mfma_f32_16x16x32_bf16 v[72:75], v[118:121], v[208:211], v[72:75]
	v_mfma_f32_16x16x32_bf16 v[4:7], v[130:133], v[208:211], v[4:7]
	v_mfma_f32_16x16x32_bf16 v[92:95], v[122:125], v[166:169], v[92:95]
	v_mfma_f32_16x16x32_bf16 v[28:31], v[134:137], v[166:169], v[28:31]
	v_mfma_f32_16x16x32_bf16 v[84:87], v[122:125], v[186:189], v[84:87]
	v_mfma_f32_16x16x32_bf16 v[20:23], v[134:137], v[186:189], v[20:23]
	v_mfma_f32_16x16x32_bf16 v[76:79], v[122:125], v[204:207], v[76:79]
	v_mfma_f32_16x16x32_bf16 v[12:15], v[134:137], v[204:207], v[12:15]
	v_mfma_f32_16x16x32_bf16 v[72:75], v[122:125], v[212:215], v[72:75]
	v_mfma_f32_16x16x32_bf16 v[4:7], v[134:137], v[212:215], v[4:7]
	s_setprio 0
	s_setprio 1
	v_mfma_f32_16x16x32_bf16 v[88:91], v[138:141], v[162:165], v[88:91]
	v_mfma_f32_16x16x32_bf16 v[24:27], v[146:149], v[162:165], v[24:27]
	v_mfma_f32_16x16x32_bf16 v[80:83], v[138:141], v[170:173], v[80:83]
	v_mfma_f32_16x16x32_bf16 v[16:19], v[146:149], v[170:173], v[16:19]
	v_mfma_f32_16x16x32_bf16 v[68:71], v[138:141], v[200:203], v[68:71]
	v_mfma_f32_16x16x32_bf16 v[8:11], v[146:149], v[200:203], v[8:11]
	v_mfma_f32_16x16x32_bf16 v[64:67], v[138:141], v[208:211], v[64:67]
	v_mfma_f32_16x16x32_bf16 v[0:3], v[146:149], v[208:211], v[0:3]
	v_mfma_f32_16x16x32_bf16 v[88:91], v[142:145], v[166:169], v[88:91]
	v_mfma_f32_16x16x32_bf16 v[24:27], v[150:153], v[166:169], v[24:27]
	v_mfma_f32_16x16x32_bf16 v[80:83], v[142:145], v[186:189], v[80:83]
	v_mfma_f32_16x16x32_bf16 v[16:19], v[150:153], v[186:189], v[16:19]
	v_mfma_f32_16x16x32_bf16 v[68:71], v[142:145], v[204:207], v[68:71]
	v_mfma_f32_16x16x32_bf16 v[8:11], v[150:153], v[204:207], v[8:11]
	v_mfma_f32_16x16x32_bf16 v[64:67], v[142:145], v[212:215], v[64:67]
	v_mfma_f32_16x16x32_bf16 v[0:3], v[150:153], v[212:215], v[0:3]
	s_barrier
	s_setprio 0
	s_add_i32 s45, s45, 2
	s_add_u32 s8, s8, 0x10000
	s_addc_u32 s9, s9, 0
	s_add_u32 s33, s33, 0x100
	s_addc_u32 s43, s43, 0
	s_cmp_gt_u32 s45, 61
	s_cbranch_scc0 .LBB0_778
	s_and_b64 vcc, exec, s[40:41]
	s_cbranch_vccz .LBB0_781
	s_barrier

; #define PG8_STAGE(bufoff, gbase, voff) do { const __amdgpu_buffer_rsrc_t _rs = __builtin_amdgcn_make_buffer_rsrc((void*)(gbase), 0, 0x7fffffff, 0x00020000); _Pragma("unroll") for (int _i = 0; _i < 2; ++_i) \
;         __builtin_amdgcn_raw_ptr_buffer_load_lds(_rs, (LAS unsigned*)(lds + (bufoff) + ldsw + _i * 8192), 16, (int)(voff)[_i], 0, 0, 0); } while (0)
; #define PG8_WAIT_V(n) asm volatile("s_waitcnt vmcnt(" #n ")" ::: "memory")
; #define PG8_WAIT_L(n) asm volatile("s_waitcnt lgkmcnt(" #n ")" ::: "memory")
; #define PG8_BAR __builtin_amdgcn_s_barrier()
; #define PG8_SCHED __builtin_amdgcn_sched_barrier(0)
; template <class Epi, class Sched, bool F8 = false>
; __device__ __forceinline__ void gemm_phase(LAS unsigned char* lds, const int lda, const int ldb, const Sched& S, const Epi& E) {
;     ...
;             const char* a1 = cA + (size_t)(t + 1) * kstep;
;             const char* a2 = last ? nA : cA + (size_t)(t + 2) * kstep; const char* b2 = last ? nB : cB + (size_t)(t + 2) * kstepB;
;             const char* a3 = a2 + kstep; const char* b3 = b2 + kstepB;
;     ...
;             PG8_LDB(B0, 0, 0); PG8_LDB(B1, 0, 1); PG8_SCHED; PG8_LDA(At, 0, 0); PG8_STAGE(PG8_SA(1, 1), a1 + hstepA, voffA);
;             PG8_WAIT_V(8); PG8_WAIT_L(0); PG8_BAR; PG8_MMA(0, 0, At, B0); PG8_MMA(0, 1, At, B1); PG8_BAR; PG8_SCHED;
;             PG8_LDA(At, 0, 1); PG8_STAGE(PG8_SB(0, 0), b2, voffB); PG8_STAGE(PG8_SB(0, 1), b2 + hstepB, voffB); PG8_STAGE(PG8_SA(0, 0), a2, voffA);
;             PG8_WAIT_V(8); PG8_WAIT_L(0); PG8_BAR; PG8_MMA(1, 0, At, B0); PG8_MMA(1, 1, At, B1); PG8_BAR; PG8_SCHED;
.LBB0_935:
	ds_read_b128 v[136:139], v142
	ds_read_b128 v[148:151], v142 offset:1024
	ds_read_b128 v[152:155], v142 offset:2048
	ds_read_b128 v[156:159], v142 offset:3072
	ds_read_b128 v[160:163], v143
	ds_read_b128 v[164:167], v143 offset:1024
	ds_read_b128 v[168:171], v143 offset:2048
	ds_read_b128 v[180:183], v143 offset:3072
	s_add_u32 s4, s91, 0xffd50080
	s_addc_u32 s5, s92, -1
	s_cmpk_eq_i32 s64, 0xa8
	s_cselect_b32 s20, s44, s4
	s_cselect_b32 s15, s45, s5
	s_cselect_b32 s14, s47, s90
	s_cselect_b32 s16, s46, s89
	s_add_u32 s12, s20, 0x80
	s_addc_u32 s13, s15, 0
	s_and_b32 s5, s92, 0xffff
	s_mov_b32 s4, s91
	s_mov_b32 m0, s79
	ds_read_b128 v[184:187], v144
	ds_read_b128 v[188:191], v144 offset:1024
	ds_read_b128 v[194:197], v144 offset:2048
	ds_read_b128 v[198:201], v144 offset:3072
	ds_read_b128 v[202:205], v144 offset:4096
	ds_read_b128 v[206:209], v144 offset:5120
	ds_read_b128 v[210:213], v144 offset:6144
	ds_read_b128 v[214:217], v144 offset:7168
	buffer_load_dwordx4 v128, s[4:7], 0 offen lds
	s_mov_b32 m0, s80
	s_nop 0
	buffer_load_dwordx4 v130, s[4:7], 0 offen lds
	s_waitcnt vmcnt(8)
	s_waitcnt lgkmcnt(0)
	s_setprio 1
	s_barrier
	v_mfma_f32_16x16x32_bf16 v[124:127], v[136:139], v[184:187], v[124:127]
	v_mfma_f32_16x16x32_bf16 v[120:123], v[152:155], v[184:187], v[120:123]
	v_mfma_f32_16x16x32_bf16 v[108:111], v[136:139], v[194:197], v[108:111]
	v_mfma_f32_16x16x32_bf16 v[104:107], v[152:155], v[194:197], v[104:107]
	v_mfma_f32_16x16x32_bf16 v[92:95], v[136:139], v[202:205], v[92:95]
	v_mfma_f32_16x16x32_bf16 v[88:91], v[152:155], v[202:205], v[88:91]
	v_mfma_f32_16x16x32_bf16 v[76:79], v[136:139], v[210:213], v[76:79]
	v_mfma_f32_16x16x32_bf16 v[72:75], v[152:155], v[210:213], v[72:75]
	v_mfma_f32_16x16x32_bf16 v[124:127], v[148:151], v[188:191], v[124:127]
	v_mfma_f32_16x16x32_bf16 v[120:123], v[156:159], v[188:191], v[120:123]
	v_mfma_f32_16x16x32_bf16 v[108:111], v[148:151], v[198:201], v[108:111]
	v_mfma_f32_16x16x32_bf16 v[104:107], v[156:159], v[198:201], v[104:107]
	v_mfma_f32_16x16x32_bf16 v[92:95], v[148:151], v[206:209], v[92:95]
	v_mfma_f32_16x16x32_bf16 v[88:91], v[156:159], v[206:209], v[88:91]
	v_mfma_f32_16x16x32_bf16 v[76:79], v[148:151], v[214:217], v[76:79]
	v_mfma_f32_16x16x32_bf16 v[72:75], v[156:159], v[214:217], v[72:75]
	s_setprio 0
	s_setprio 1
	v_mfma_f32_16x16x32_bf16 v[116:119], v[160:163], v[184:187], v[116:119]
	v_mfma_f32_16x16x32_bf16 v[112:115], v[168:171], v[184:187], v[112:115]
	v_mfma_f32_16x16x32_bf16 v[100:103], v[160:163], v[194:197], v[100:103]
	v_mfma_f32_16x16x32_bf16 v[96:99], v[168:171], v[194:197], v[96:99]
	v_mfma_f32_16x16x32_bf16 v[84:87], v[160:163], v[202:205], v[84:87]
	v_mfma_f32_16x16x32_bf16 v[80:83], v[168:171], v[202:205], v[80:83]
	v_mfma_f32_16x16x32_bf16 v[68:71], v[160:163], v[210:213], v[68:71]
	v_mfma_f32_16x16x32_bf16 v[64:67], v[168:171], v[210:213], v[64:67]
	v_mfma_f32_16x16x32_bf16 v[116:119], v[164:167], v[188:191], v[116:119]
	v_mfma_f32_16x16x32_bf16 v[112:115], v[180:183], v[188:191], v[112:115]
	v_mfma_f32_16x16x32_bf16 v[100:103], v[164:167], v[198:201], v[100:103]
	v_mfma_f32_16x16x32_bf16 v[96:99], v[180:183], v[198:201], v[96:99]
	v_mfma_f32_16x16x32_bf16 v[84:87], v[164:167], v[206:209], v[84:87]
	v_mfma_f32_16x16x32_bf16 v[80:83], v[180:183], v[206:209], v[80:83]
	v_mfma_f32_16x16x32_bf16 v[68:71], v[164:167], v[214:217], v[68:71]
	v_mfma_f32_16x16x32_bf16 v[64:67], v[180:183], v[214:217], v[64:67]
	s_barrier
	s_setprio 0
	s_and_b32 s17, s14, 0xffff
	s_mov_b32 m0, s49
	s_mov_b32 s18, s6
	s_mov_b32 s19, s7
	s_add_u32 s4, s16, 0x4000
	ds_read_b128 v[184:187], v144 offset:16384
	ds_read_b128 v[188:191], v144 offset:17408
	ds_read_b128 v[194:197], v144 offset:18432
	ds_read_b128 v[198:201], v144 offset:19456
	ds_read_b128 v[202:205], v144 offset:20480
	ds_read_b128 v[206:209], v144 offset:21504
	ds_read_b128 v[210:213], v144 offset:22528
	ds_read_b128 v[214:217], v144 offset:23552
	buffer_load_dwordx4 v129, s[16:19], 0 offen lds
	s_mov_b32 m0, s50
	s_addc_u32 s5, s14, 0
	buffer_load_dwordx4 v131, s[16:19], 0 offen lds
	s_and_b32 s5, s5, 0xffff
	s_mov_b32 m0, s51
	s_and_b32 s21, s15, 0xffff
	buffer_load_dwordx4 v129, s[4:7], 0 offen lds
	s_mov_b32 m0, s52
	s_mov_b32 s22, s6
	buffer_load_dwordx4 v131, s[4:7], 0 offen lds
	s_mov_b32 s23, s7
	s_mov_b32 m0, s48
	s_nop 0
	buffer_load_dwordx4 v128, s[20:23], 0 offen lds
	s_mov_b32 m0, s53
	s_nop 0
	buffer_load_dwordx4 v130, s[20:23], 0 offen lds
	s_waitcnt vmcnt(8)
	s_waitcnt lgkmcnt(0)
	s_setprio 1
	s_barrier
	v_mfma_f32_16x16x32_bf16 v[60:63], v[136:139], v[184:187], v[60:63]
	v_mfma_f32_16x16x32_bf16 v[56:59], v[152:155], v[184:187], v[56:59]
	v_mfma_f32_16x16x32_bf16 v[44:47], v[136:139], v[194:197], v[44:47]
	v_mfma_f32_16x16x32_bf16 v[40:43], v[152:155], v[194:197], v[40:43]
	v_mfma_f32_16x16x32_bf16 v[28:31], v[136:139], v[202:205], v[28:31]
	v_mfma_f32_16x16x32_bf16 v[24:27], v[152:155], v[202:205], v[24:27]
	v_mfma_f32_16x16x32_bf16 v[12:15], v[136:139], v[210:213], v[12:15]
	v_mfma_f32_16x16x32_bf16 v[8:11], v[152:155], v[210:213], v[8:11]
	v_mfma_f32_16x16x32_bf16 v[60:63], v[148:151], v[188:191], v[60:63]
	v_mfma_f32_16x16x32_bf16 v[56:59], v[156:159], v[188:191], v[56:59]
	v_mfma_f32_16x16x32_bf16 v[44:47], v[148:151], v[198:201], v[44:47]
	v_mfma_f32_16x16x32_bf16 v[40:43], v[156:159], v[198:201], v[40:43]
	v_mfma_f32_16x16x32_bf16 v[28:31], v[148:151], v[206:209], v[28:31]
	v_mfma_f32_16x16x32_bf16 v[24:27], v[156:159], v[206:209], v[24:27]
	v_mfma_f32_16x16x32_bf16 v[12:15], v[148:151], v[214:217], v[12:15]
	v_mfma_f32_16x16x32_bf16 v[8:11], v[156:159], v[214:217], v[8:11]
	s_setprio 0
	s_setprio 1
	v_mfma_f32_16x16x32_bf16 v[52:55], v[160:163], v[184:187], v[52:55]
	v_mfma_f32_16x16x32_bf16 v[48:51], v[168:171], v[184:187], v[48:51]
	v_mfma_f32_16x16x32_bf16 v[36:39], v[160:163], v[194:197], v[36:39]
	v_mfma_f32_16x16x32_bf16 v[32:35], v[168:171], v[194:197], v[32:35]
	v_mfma_f32_16x16x32_bf16 v[20:23], v[160:163], v[202:205], v[20:23]
	v_mfma_f32_16x16x32_bf16 v[16:19], v[168:171], v[202:205], v[16:19]
	v_mfma_f32_16x16x32_bf16 v[4:7], v[160:163], v[210:213], v[4:7]
	v_mfma_f32_16x16x32_bf16 v[0:3], v[168:171], v[210:213], v[0:3]
	v_mfma_f32_16x16x32_bf16 v[52:55], v[164:167], v[188:191], v[52:55]
	v_mfma_f32_16x16x32_bf16 v[48:51], v[180:183], v[188:191], v[48:51]
	v_mfma_f32_16x16x32_bf16 v[36:39], v[164:167], v[198:201], v[36:39]
	v_mfma_f32_16x16x32_bf16 v[32:35], v[180:183], v[198:201], v[32:35]
	v_mfma_f32_16x16x32_bf16 v[20:23], v[164:167], v[206:209], v[20:23]
	v_mfma_f32_16x16x32_bf16 v[16:19], v[180:183], v[206:209], v[16:19]
	v_mfma_f32_16x16x32_bf16 v[4:7], v[164:167], v[214:217], v[4:7]
	v_mfma_f32_16x16x32_bf16 v[0:3], v[180:183], v[214:217], v[0:3]
	s_barrier
; #define PG8_STAGE(bufoff, gbase, voff) do { const __amdgpu_buffer_rsrc_t _rs = __builtin_amdgcn_make_buffer_rsrc((void*)(gbase), 0, 0x7fffffff, 0x00020000); _Pragma("unroll") for (int _i = 0; _i < 2; ++_i) \
;         __builtin_amdgcn_raw_ptr_buffer_load_lds(_rs, (LAS unsigned*)(lds + (bufoff) + ldsw + _i * 8192), 16, (int)(voff)[_i], 0, 0, 0); } while (0)
; #define PG8_WAIT_V(n) asm volatile("s_waitcnt vmcnt(" #n ")" ::: "memory")
; #define PG8_WAIT_L(n) asm volatile("s_waitcnt lgkmcnt(" #n ")" ::: "memory")
; #define PG8_BAR __builtin_amdgcn_s_barrier()
; #define PG8_SCHED __builtin_amdgcn_sched_barrier(0)
; template <class Epi, class Sched, bool F8 = false>
; __device__ __forceinline__ void gemm_phase(LAS unsigned char* lds, const int lda, const int ldb, const Sched& S, const Epi& E) {
;     ...
;             PG8_LDB(B0, 1, 0); PG8_LDB(B1, 1, 1); PG8_SCHED; PG8_LDA(At, 1, 0); PG8_STAGE(PG8_SA(0, 1), a2 + hstepA, voffA);
;             PG8_WAIT_V(8); PG8_WAIT_L(0); PG8_BAR; PG8_MMA(0, 0, At, B0); PG8_MMA(0, 1, At, B1); PG8_BAR; PG8_SCHED;
;             PG8_LDA(At, 1, 1); PG8_STAGE(PG8_SB(1, 0), b3, voffB); PG8_STAGE(PG8_SB(1, 1), b3 + hstepB, voffB); PG8_STAGE(PG8_SA(1, 0), a3, voffA);
;             PG8_WAIT_V(8); PG8_WAIT_L(0); PG8_BAR; PG8_MMA(1, 0, At, B0); PG8_MMA(1, 1, At, B1); PG8_BAR; PG8_SCHED;
	s_setprio 0
	ds_read_b128 v[136:139], v145
	ds_read_b128 v[148:151], v145 offset:1024
	ds_read_b128 v[152:155], v145 offset:2048
	ds_read_b128 v[156:159], v145 offset:3072
	ds_read_b128 v[160:163], v146
	ds_read_b128 v[164:167], v146 offset:1024
	ds_read_b128 v[168:171], v146 offset:2048
	ds_read_b128 v[180:183], v146 offset:3072
	s_add_u32 s4, s20, 0x2b0000
	s_addc_u32 s5, s15, 0
	s_and_b32 s5, s5, 0xffff
	s_mov_b32 m0, s61
	ds_read_b128 v[184:187], v144 offset:32768
	ds_read_b128 v[188:191], v144 offset:33792
	ds_read_b128 v[194:197], v144 offset:34816
	ds_read_b128 v[198:201], v144 offset:35840
	ds_read_b128 v[202:205], v144 offset:36864
	ds_read_b128 v[206:209], v144 offset:37888
	ds_read_b128 v[210:213], v144 offset:38912
	ds_read_b128 v[214:217], v144 offset:39936
	buffer_load_dwordx4 v128, s[4:7], 0 offen lds
	s_mov_b32 m0, s66
	s_nop 0
	buffer_load_dwordx4 v130, s[4:7], 0 offen lds
	s_waitcnt vmcnt(8)
	s_waitcnt lgkmcnt(0)
	s_setprio 1
	s_barrier
	v_mfma_f32_16x16x32_bf16 v[124:127], v[136:139], v[184:187], v[124:127]
	v_mfma_f32_16x16x32_bf16 v[120:123], v[152:155], v[184:187], v[120:123]
	v_mfma_f32_16x16x32_bf16 v[108:111], v[136:139], v[194:197], v[108:111]
	v_mfma_f32_16x16x32_bf16 v[104:107], v[152:155], v[194:197], v[104:107]
	v_mfma_f32_16x16x32_bf16 v[92:95], v[136:139], v[202:205], v[92:95]
	v_mfma_f32_16x16x32_bf16 v[88:91], v[152:155], v[202:205], v[88:91]
	v_mfma_f32_16x16x32_bf16 v[76:79], v[136:139], v[210:213], v[76:79]
	v_mfma_f32_16x16x32_bf16 v[72:75], v[152:155], v[210:213], v[72:75]
	v_mfma_f32_16x16x32_bf16 v[124:127], v[148:151], v[188:191], v[124:127]
	v_mfma_f32_16x16x32_bf16 v[120:123], v[156:159], v[188:191], v[120:123]
	v_mfma_f32_16x16x32_bf16 v[108:111], v[148:151], v[198:201], v[108:111]
	v_mfma_f32_16x16x32_bf16 v[104:107], v[156:159], v[198:201], v[104:107]
	v_mfma_f32_16x16x32_bf16 v[92:95], v[148:151], v[206:209], v[92:95]
	v_mfma_f32_16x16x32_bf16 v[88:91], v[156:159], v[206:209], v[88:91]
	v_mfma_f32_16x16x32_bf16 v[76:79], v[148:151], v[214:217], v[76:79]
	v_mfma_f32_16x16x32_bf16 v[72:75], v[156:159], v[214:217], v[72:75]
	s_setprio 0
	s_setprio 1
	v_mfma_f32_16x16x32_bf16 v[116:119], v[160:163], v[184:187], v[116:119]
	v_mfma_f32_16x16x32_bf16 v[112:115], v[168:171], v[184:187], v[112:115]
	v_mfma_f32_16x16x32_bf16 v[100:103], v[160:163], v[194:197], v[100:103]
	v_mfma_f32_16x16x32_bf16 v[96:99], v[168:171], v[194:197], v[96:99]
	v_mfma_f32_16x16x32_bf16 v[84:87], v[160:163], v[202:205], v[84:87]
	v_mfma_f32_16x16x32_bf16 v[80:83], v[168:171], v[202:205], v[80:83]
	v_mfma_f32_16x16x32_bf16 v[68:71], v[160:163], v[210:213], v[68:71]
	v_mfma_f32_16x16x32_bf16 v[64:67], v[168:171], v[210:213], v[64:67]
	v_mfma_f32_16x16x32_bf16 v[116:119], v[164:167], v[188:191], v[116:119]
	v_mfma_f32_16x16x32_bf16 v[112:115], v[180:183], v[188:191], v[112:115]
	v_mfma_f32_16x16x32_bf16 v[100:103], v[164:167], v[198:201], v[100:103]
	v_mfma_f32_16x16x32_bf16 v[96:99], v[180:183], v[198:201], v[96:99]
	v_mfma_f32_16x16x32_bf16 v[84:87], v[164:167], v[206:209], v[84:87]
	v_mfma_f32_16x16x32_bf16 v[80:83], v[180:183], v[206:209], v[80:83]
	v_mfma_f32_16x16x32_bf16 v[68:71], v[164:167], v[214:217], v[68:71]
	v_mfma_f32_16x16x32_bf16 v[64:67], v[180:183], v[214:217], v[64:67]
	s_barrier
	s_setprio 0
	s_add_u32 s4, s16, 0x8000
	s_addc_u32 s5, s14, 0
	s_mov_b32 m0, s73
	s_and_b32 s5, s5, 0xffff
	ds_read_b128 v[184:187], v144 offset:49152
	ds_read_b128 v[188:191], v144 offset:50176
	ds_read_b128 v[194:197], v144 offset:51200
	ds_read_b128 v[198:201], v144 offset:52224
	ds_read_b128 v[202:205], v144 offset:53248
	ds_read_b128 v[206:209], v144 offset:54272
	ds_read_b128 v[210:213], v144 offset:55296
	ds_read_b128 v[214:217], v144 offset:56320
	buffer_load_dwordx4 v129, s[4:7], 0 offen lds
	s_mov_b32 m0, s74
	s_mov_b32 s15, s7
	buffer_load_dwordx4 v131, s[4:7], 0 offen lds
	s_add_u32 s4, s16, 0xc000
	s_addc_u32 s5, s14, 0
	s_and_b32 s5, s5, 0xffff
	s_mov_b32 m0, s77
	s_and_b32 s13, s13, 0xffff
	buffer_load_dwordx4 v129, s[4:7], 0 offen lds
	s_mov_b32 m0, s78
	s_mov_b32 s14, s6
	buffer_load_dwordx4 v131, s[4:7], 0 offen lds
	s_mov_b32 m0, s75
	s_nop 0
	buffer_load_dwordx4 v128, s[12:15], 0 offen lds
	s_mov_b32 m0, s76
	s_nop 0
	buffer_load_dwordx4 v130, s[12:15], 0 offen lds
	s_waitcnt vmcnt(8)
	s_waitcnt lgkmcnt(0)
	s_setprio 1
	s_barrier
	v_mfma_f32_16x16x32_bf16 v[60:63], v[136:139], v[184:187], v[60:63]
	v_mfma_f32_16x16x32_bf16 v[56:59], v[152:155], v[184:187], v[56:59]
	v_mfma_f32_16x16x32_bf16 v[44:47], v[136:139], v[194:197], v[44:47]
	v_mfma_f32_16x16x32_bf16 v[40:43], v[152:155], v[194:197], v[40:43]
	v_mfma_f32_16x16x32_bf16 v[28:31], v[136:139], v[202:205], v[28:31]
	v_mfma_f32_16x16x32_bf16 v[24:27], v[152:155], v[202:205], v[24:27]
	v_mfma_f32_16x16x32_bf16 v[12:15], v[136:139], v[210:213], v[12:15]
	v_mfma_f32_16x16x32_bf16 v[8:11], v[152:155], v[210:213], v[8:11]
	v_mfma_f32_16x16x32_bf16 v[60:63], v[148:151], v[188:191], v[60:63]
	v_mfma_f32_16x16x32_bf16 v[56:59], v[156:159], v[188:191], v[56:59]
	v_mfma_f32_16x16x32_bf16 v[44:47], v[148:151], v[198:201], v[44:47]
	v_mfma_f32_16x16x32_bf16 v[40:43], v[156:159], v[198:201], v[40:43]
	v_mfma_f32_16x16x32_bf16 v[28:31], v[148:151], v[206:209], v[28:31]
	v_mfma_f32_16x16x32_bf16 v[24:27], v[156:159], v[206:209], v[24:27]
	v_mfma_f32_16x16x32_bf16 v[12:15], v[148:151], v[214:217], v[12:15]
	v_mfma_f32_16x16x32_bf16 v[8:11], v[156:159], v[214:217], v[8:11]
	s_setprio 0
	s_setprio 1
	v_mfma_f32_16x16x32_bf16 v[52:55], v[160:163], v[184:187], v[52:55]
	v_mfma_f32_16x16x32_bf16 v[48:51], v[168:171], v[184:187], v[48:51]
	v_mfma_f32_16x16x32_bf16 v[36:39], v[160:163], v[194:197], v[36:39]
	v_mfma_f32_16x16x32_bf16 v[32:35], v[168:171], v[194:197], v[32:35]
	v_mfma_f32_16x16x32_bf16 v[20:23], v[160:163], v[202:205], v[20:23]
	v_mfma_f32_16x16x32_bf16 v[16:19], v[168:171], v[202:205], v[16:19]
	v_mfma_f32_16x16x32_bf16 v[4:7], v[160:163], v[210:213], v[4:7]
	v_mfma_f32_16x16x32_bf16 v[0:3], v[168:171], v[210:213], v[0:3]
	v_mfma_f32_16x16x32_bf16 v[52:55], v[164:167], v[188:191], v[52:55]
	v_mfma_f32_16x16x32_bf16 v[48:51], v[180:183], v[188:191], v[48:51]
	v_mfma_f32_16x16x32_bf16 v[36:39], v[164:167], v[198:201], v[36:39]
	v_mfma_f32_16x16x32_bf16 v[32:35], v[180:183], v[198:201], v[32:35]
	v_mfma_f32_16x16x32_bf16 v[20:23], v[164:167], v[206:209], v[20:23]
	v_mfma_f32_16x16x32_bf16 v[16:19], v[180:183], v[206:209], v[16:19]
	v_mfma_f32_16x16x32_bf16 v[4:7], v[164:167], v[214:217], v[4:7]
	v_mfma_f32_16x16x32_bf16 v[0:3], v[180:183], v[214:217], v[0:3]
	s_barrier
	s_setprio 0
	s_add_i32 s64, s64, 2
	s_add_u32 s89, s89, 0x10000
	s_addc_u32 s90, s90, 0
	s_add_u32 s91, s91, 0x100
	s_addc_u32 s92, s92, 0
	s_cmpk_gt_u32 s64, 0xa9
	s_cbranch_scc0 .LBB0_935
	s_and_b64 vcc, exec, s[30:31]
	s_cbranch_vccz .LBB0_938
	s_barrier
